# sc1 (write-through) on the attention Y stores of NA/MEM/B finalize: less dirty L2 at the grid barriers
# baseline (speedup 1.0000x reference)
.LBB0_496:
	s_waitcnt lgkmcnt(0)
	v_add_f32_e32 v0, v68, v69
	v_rcp_f32_e32 v66, v0
	s_ashr_i32 s0, s58, 5
	s_lshl_b32 s10, s58, 8
	s_ashr_i32 s1, s0, 31
	s_and_b32 s10, s10, 0x700
	s_lshl_b64 s[0:1], s[0:1], 11
	s_add_i32 s10, s10, s31
	v_pk_mul_f32 v[34:35], v[34:35], v[66:67] op_sel_hi:[1,0]
	v_pk_mul_f32 v[36:37], v[36:37], v[66:67] op_sel_hi:[1,0]
	s_add_u32 s16, s0, s10
	v_cvt_pk_bf16_f32 v34, v34, v35
	v_cvt_pk_bf16_f32 v35, v36, v37
	v_pk_mul_f32 v[36:37], v[38:39], v[66:67] op_sel_hi:[1,0]
	v_pk_mul_f32 v[38:39], v[40:41], v[66:67] op_sel_hi:[1,0]
	s_addc_u32 s0, s1, 0
	v_cvt_pk_bf16_f32 v36, v36, v37
	v_cvt_pk_bf16_f32 v37, v38, v39
	s_lshl_b32 s1, s58, 5
	v_pk_mul_f32 v[50:51], v[50:51], v[66:67] op_sel_hi:[1,0]
	v_pk_mul_f32 v[52:53], v[52:53], v[66:67] op_sel_hi:[1,0]
	ds_write2_b64 v197, v[34:35], v[36:37] offset0:8 offset1:10
	v_pk_mul_f32 v[34:35], v[42:43], v[66:67] op_sel_hi:[1,0]
	v_pk_mul_f32 v[36:37], v[44:45], v[66:67] op_sel_hi:[1,0]
	s_and_b32 s10, s1, 0x300
	v_cvt_pk_bf16_f32 v50, v50, v51
	v_cvt_pk_bf16_f32 v51, v52, v53
	v_pk_mul_f32 v[52:53], v[54:55], v[66:67] op_sel_hi:[1,0]
	v_pk_mul_f32 v[54:55], v[56:57], v[66:67] op_sel_hi:[1,0]
	v_cvt_pk_bf16_f32 v34, v34, v35
	v_cvt_pk_bf16_f32 v35, v36, v37
	v_pk_mul_f32 v[36:37], v[46:47], v[66:67] op_sel_hi:[1,0]
	v_pk_mul_f32 v[38:39], v[48:49], v[66:67] op_sel_hi:[1,0]
	s_add_u32 s14, s96, s10
	v_cvt_pk_bf16_f32 v52, v52, v53
	v_cvt_pk_bf16_f32 v53, v54, v55
	v_cvt_pk_bf16_f32 v36, v36, v37
	v_cvt_pk_bf16_f32 v37, v38, v39
	s_addc_u32 s15, s97, 0
	ds_write2_b64 v197, v[50:51], v[52:53] offset1:2
	v_pk_mul_f32 v[50:51], v[58:59], v[66:67] op_sel_hi:[1,0]
	v_pk_mul_f32 v[52:53], v[60:61], v[66:67] op_sel_hi:[1,0]
	v_pk_mul_f32 v[54:55], v[64:65], v[66:67] op_sel_hi:[1,0]
	ds_write2_b64 v197, v[34:35], v[36:37] offset0:12 offset1:14
	v_or_b32_e32 v64, s16, v164
	v_mov_b64_e32 v[34:35], s[14:15]
	v_cvt_pk_bf16_f32 v50, v50, v51
	v_cvt_pk_bf16_f32 v51, v52, v53
	v_pk_mul_f32 v[52:53], v[62:63], v[66:67] op_sel_hi:[1,0]
	v_mad_u64_u32 v[36:37], s[14:15], v64, s43, v[34:35]
	v_cvt_pk_bf16_f32 v52, v52, v53
	v_cvt_pk_bf16_f32 v53, v54, v55
	v_mad_i32_i24 v37, s0, v211, v37
	s_mov_b64 s[24:25], 0x3400
	ds_write2_b64 v197, v[50:51], v[52:53] offset0:4 offset1:6
	v_lshl_add_u64 v[42:43], v[36:37], 0, s[24:25]
	v_lshlrev_b32_e32 v0, 1, v166
	s_waitcnt lgkmcnt(0)
	v_lshl_add_u64 v[36:37], v[42:43], 0, v[0:1]
	global_load_dwordx4 v[50:53], v[36:37], off
	v_or_b32_e32 v72, s16, v168
	v_mad_u64_u32 v[36:37], s[14:15], v72, s43, v[34:35]
	v_mad_i32_i24 v37, s0, v211, v37
	v_lshl_add_u64 v[48:49], v[36:37], 0, s[24:25]
	v_lshl_add_u64 v[36:37], v[48:49], 0, v[0:1]
	global_load_dwordx4 v[68:71], v[36:37], off
	v_or_b32_e32 v56, s16, v170
	v_or_b32_e32 v54, s16, v172
	v_mad_u64_u32 v[38:39], s[14:15], v56, s43, v[34:35]
	v_mad_u64_u32 v[34:35], s[14:15], v54, s43, v[34:35]
	v_mad_i32_i24 v39, s0, v211, v39
	v_mad_i32_i24 v35, s0, v211, v35
	v_lshl_add_u64 v[44:45], v[38:39], 0, s[24:25]
	v_lshl_add_u64 v[46:47], v[34:35], 0, s[24:25]
	v_add_u32_e32 v58, v185, v186
	v_lshl_add_u64 v[34:35], v[44:45], 0, v[0:1]
	v_lshl_add_u64 v[36:37], v[46:47], 0, v[0:1]
	ds_read_b128 v[60:63], v58
	global_load_dwordx4 v[38:41], v[34:35], off
	s_nop 0
	global_load_dwordx4 v[34:37], v[36:37], off
	v_lshlrev_b32_e32 v232, 1, v174
	v_mov_b32_e32 v233, 0
	v_lshl_add_u64 v[234:235], v[42:43], 0, v[232:233]
	global_load_dwordx4 v[216:219], v[234:235], off
	v_lshl_add_u64 v[234:235], v[48:49], 0, v[232:233]
	global_load_dwordx4 v[220:223], v[234:235], off
	v_lshl_add_u64 v[234:235], v[44:45], 0, v[232:233]
	global_load_dwordx4 v[224:227], v[234:235], off
	v_lshl_add_u64 v[234:235], v[46:47], 0, v[232:233]
	global_load_dwordx4 v[228:231], v[234:235], off
	v_mov_b32_e32 v65, s0
	s_mov_b32 s11, s99
	v_mov_b32_e32 v73, s0
	s_waitcnt lgkmcnt(0)
	v_lshlrev_b32_e32 v74, 16, v60
	v_and_b32_e32 v75, 0xffff0000, v60
	v_lshlrev_b32_e32 v60, 16, v61
	v_and_b32_e32 v61, 0xffff0000, v61
	v_pk_mul_f32 v[18:19], v[18:19], v[66:67] op_sel_hi:[1,0]
	v_pk_mul_f32 v[20:21], v[20:21], v[66:67] op_sel_hi:[1,0]
	v_pk_mul_f32 v[2:3], v[2:3], v[66:67] op_sel_hi:[1,0]
	v_pk_mul_f32 v[4:5], v[4:5], v[66:67] op_sel_hi:[1,0]
	v_cvt_pk_bf16_f32 v18, v18, v19
	v_cvt_pk_bf16_f32 v19, v20, v21
	v_pk_mul_f32 v[20:21], v[22:23], v[66:67] op_sel_hi:[1,0]
	v_pk_mul_f32 v[22:23], v[24:25], v[66:67] op_sel_hi:[1,0]
	v_cvt_pk_bf16_f32 v2, v2, v3
	v_cvt_pk_bf16_f32 v3, v4, v5
	v_pk_mul_f32 v[4:5], v[6:7], v[66:67] op_sel_hi:[1,0]
	v_pk_mul_f32 v[6:7], v[8:9], v[66:67] op_sel_hi:[1,0]
	v_cvt_pk_bf16_f32 v20, v20, v21
	v_cvt_pk_bf16_f32 v21, v22, v23
	v_cvt_pk_bf16_f32 v4, v4, v5
	v_cvt_pk_bf16_f32 v5, v6, v7
	v_pk_mul_f32 v[22:23], v[32:33], v[66:67] op_sel_hi:[1,0]
	v_pk_mul_f32 v[6:7], v[16:17], v[66:67] op_sel_hi:[1,0]
	s_waitcnt vmcnt(0)
	v_lshlrev_b32_e32 v76, 16, v50
	v_and_b32_e32 v77, 0xffff0000, v50
	v_mul_f32_e32 v55, 0xbfb8aa3b, v76
	v_mul_f32_e32 v57, 0xbfb8aa3b, v77
	v_exp_f32_e32 v55, v55
	v_exp_f32_e32 v57, v57
	v_lshlrev_b32_e32 v50, 16, v51
	v_and_b32_e32 v51, 0xffff0000, v51
	v_add_f32_e32 v55, 1.0, v55
	v_add_f32_e32 v57, 1.0, v57
	v_rcp_f32_e32 v78, v55
	v_rcp_f32_e32 v79, v57
	v_mul_f32_e32 v55, 0xbfb8aa3b, v51
	v_mul_f32_e32 v59, 0xbfb8aa3b, v50
	v_exp_f32_e32 v55, v55
	v_exp_f32_e32 v59, v59
	v_pk_mul_f32 v[76:77], v[78:79], v[76:77]
	v_add_f32_e32 v55, 1.0, v55
	v_pk_mul_f32 v[74:75], v[76:77], v[74:75]
	v_lshlrev_b32_e32 v76, 16, v52
	v_and_b32_e32 v77, 0xffff0000, v52
	v_mul_f32_e32 v52, 0xbfb8aa3b, v76
	v_add_f32_e32 v57, 1.0, v59
	v_rcp_f32_e32 v79, v55
	v_exp_f32_e32 v52, v52
	v_mul_f32_e32 v55, 0xbfb8aa3b, v77
	v_rcp_f32_e32 v78, v57
	v_exp_f32_e32 v55, v55
	v_add_f32_e32 v52, 1.0, v52
	v_pk_mul_f32 v[50:51], v[78:79], v[50:51]
	v_rcp_f32_e32 v78, v52
	v_add_f32_e32 v52, 1.0, v55
	v_rcp_f32_e32 v79, v52
	v_lshlrev_b32_e32 v52, 16, v53
	v_and_b32_e32 v53, 0xffff0000, v53
	v_mul_f32_e32 v55, 0xbfb8aa3b, v52
	v_exp_f32_e32 v55, v55
	v_mul_f32_e32 v57, 0xbfb8aa3b, v53
	v_exp_f32_e32 v57, v57
	v_pk_mul_f32 v[76:77], v[78:79], v[76:77]
	v_add_f32_e32 v55, 1.0, v55
	v_rcp_f32_e32 v78, v55
	v_add_f32_e32 v55, 1.0, v57
	v_rcp_f32_e32 v79, v55
	v_pk_mul_f32 v[50:51], v[50:51], v[60:61]
	v_lshlrev_b32_e32 v60, 16, v62
	v_and_b32_e32 v61, 0xffff0000, v62
	v_pk_mul_f32 v[76:77], v[76:77], v[60:61]
	v_lshlrev_b32_e32 v60, 16, v63
	v_and_b32_e32 v61, 0xffff0000, v63
	v_pk_mul_f32 v[52:53], v[78:79], v[52:53]
	v_cvt_pk_bf16_f32 v62, v76, v77
	v_pk_mul_f32 v[52:53], v[52:53], v[60:61]
	v_cvt_pk_bf16_f32 v61, v50, v51
	v_lshlrev_b64 v[50:51], 12, v[64:65]
	v_lshlrev_b32_e32 v64, 16, v68
	v_cvt_pk_bf16_f32 v63, v52, v53
	v_and_b32_e32 v65, 0xffff0000, v68
	v_mul_f32_e32 v53, 0xbfb8aa3b, v64
	v_exp_f32_e32 v55, v53
	v_mul_f32_e32 v53, 0xbfb8aa3b, v65
	v_exp_f32_e32 v57, v53
	v_cvt_pk_bf16_f32 v60, v74, v75
	v_add_f32_e32 v55, 1.0, v55
	v_rcp_f32_e32 v74, v55
	v_add_f32_e32 v55, 1.0, v57
	v_lshlrev_b32_e32 v68, 16, v69
	v_rcp_f32_e32 v75, v55
	v_and_b32_e32 v69, 0xffff0000, v69
	v_mul_f32_e32 v55, 0xbfb8aa3b, v68
	v_lshl_add_u64 v[50:51], s[90:91], 0, v[50:51]
	v_exp_f32_e32 v55, v55
	v_mul_f32_e32 v57, 0xbfb8aa3b, v69
	v_lshl_add_u64 v[50:51], v[50:51], 0, s[10:11]
	v_exp_f32_e32 v57, v57
	v_lshl_add_u64 v[50:51], v[50:51], 0, v[0:1]
	global_store_dwordx4 v[50:51], v[60:63], off offset:3072 sc1
	ds_read_b128 v[60:63], v58 offset:1152
	v_add_f32_e32 v55, 1.0, v55
	v_pk_mul_f32 v[64:65], v[74:75], v[64:65]
	v_rcp_f32_e32 v74, v55
	v_add_f32_e32 v55, 1.0, v57
	v_rcp_f32_e32 v75, v55
	s_waitcnt lgkmcnt(0)
	v_lshlrev_b32_e32 v52, 16, v60
	v_and_b32_e32 v53, 0xffff0000, v60
	v_pk_mul_f32 v[52:53], v[64:65], v[52:53]
	v_pk_mul_f32 v[64:65], v[74:75], v[68:69]
	v_lshlrev_b32_e32 v68, 16, v70
	v_and_b32_e32 v69, 0xffff0000, v70
	v_mul_f32_e32 v55, 0xbfb8aa3b, v68
	v_exp_f32_e32 v55, v55
	v_mul_f32_e32 v57, 0xbfb8aa3b, v69
	v_exp_f32_e32 v57, v57
	v_lshlrev_b32_e32 v70, 16, v71
	v_add_f32_e32 v55, 1.0, v55
	v_rcp_f32_e32 v74, v55
	v_add_f32_e32 v55, 1.0, v57
	v_rcp_f32_e32 v75, v55
	v_and_b32_e32 v71, 0xffff0000, v71
	v_mul_f32_e32 v55, 0xbfb8aa3b, v70
	v_exp_f32_e32 v55, v55
	v_mul_f32_e32 v57, 0xbfb8aa3b, v71
	v_exp_f32_e32 v57, v57
	v_pk_mul_f32 v[68:69], v[74:75], v[68:69]
	v_add_f32_e32 v55, 1.0, v55
	v_rcp_f32_e32 v74, v55
	v_add_f32_e32 v55, 1.0, v57
	v_rcp_f32_e32 v75, v55
	v_lshlrev_b32_e32 v60, 16, v61
	v_and_b32_e32 v61, 0xffff0000, v61
	v_pk_mul_f32 v[64:65], v[64:65], v[60:61]
	v_lshlrev_b32_e32 v60, 16, v62
	v_and_b32_e32 v61, 0xffff0000, v62
	v_pk_mul_f32 v[68:69], v[68:69], v[60:61]
	v_lshlrev_b32_e32 v60, 16, v63
	v_and_b32_e32 v61, 0xffff0000, v63
	v_pk_mul_f32 v[62:63], v[74:75], v[70:71]
	v_mov_b32_e32 v57, s0
	v_pk_mul_f32 v[70:71], v[62:63], v[60:61]
	v_cvt_pk_bf16_f32 v62, v68, v69
	v_lshlrev_b32_e32 v68, 16, v38
	v_and_b32_e32 v69, 0xffff0000, v38
	v_mul_f32_e32 v38, 0xbfb8aa3b, v68
	v_exp_f32_e32 v38, v38
	v_mul_f32_e32 v55, 0xbfb8aa3b, v69
	v_cvt_pk_bf16_f32 v60, v52, v53
	v_lshlrev_b64 v[52:53], 12, v[72:73]
	v_exp_f32_e32 v55, v55
	v_lshl_add_u64 v[52:53], s[90:91], 0, v[52:53]
	v_lshl_add_u64 v[52:53], v[52:53], 0, s[10:11]
	v_cvt_pk_bf16_f32 v61, v64, v65
	v_cvt_pk_bf16_f32 v63, v70, v71
	v_lshl_add_u64 v[52:53], v[52:53], 0, v[0:1]
	v_add_f32_e32 v38, 1.0, v38
	global_store_dwordx4 v[52:53], v[60:63], off offset:3072 sc1
	v_rcp_f32_e32 v70, v38
	v_add_f32_e32 v38, 1.0, v55
	ds_read_b128 v[60:63], v58 offset:2304
	v_rcp_f32_e32 v71, v38
	v_lshlrev_b32_e32 v38, 16, v39
	v_and_b32_e32 v39, 0xffff0000, v39
	v_mul_f32_e32 v55, 0xbfb8aa3b, v38
	v_exp_f32_e32 v55, v55
	v_mul_f32_e32 v59, 0xbfb8aa3b, v39
	v_exp_f32_e32 v59, v59
	s_waitcnt lgkmcnt(0)
	v_lshlrev_b32_e32 v64, 16, v60
	v_and_b32_e32 v65, 0xffff0000, v60
	v_pk_mul_f32 v[68:69], v[70:71], v[68:69]
	v_add_f32_e32 v55, 1.0, v55
	v_pk_mul_f32 v[64:65], v[68:69], v[64:65]
	v_lshlrev_b32_e32 v68, 16, v40
	v_rcp_f32_e32 v70, v55
	v_add_f32_e32 v55, 1.0, v59
	v_and_b32_e32 v69, 0xffff0000, v40
	v_mul_f32_e32 v40, 0xbfb8aa3b, v68
	v_rcp_f32_e32 v71, v55
	v_exp_f32_e32 v40, v40
	v_mul_f32_e32 v55, 0xbfb8aa3b, v69
	v_exp_f32_e32 v55, v55
	v_pk_mul_f32 v[38:39], v[70:71], v[38:39]
	v_add_f32_e32 v40, 1.0, v40
	v_rcp_f32_e32 v70, v40
	v_add_f32_e32 v40, 1.0, v55
	v_rcp_f32_e32 v71, v40
	v_lshlrev_b32_e32 v40, 16, v41
	v_and_b32_e32 v41, 0xffff0000, v41
	v_mul_f32_e32 v55, 0xbfb8aa3b, v40
	v_exp_f32_e32 v55, v55
	v_mul_f32_e32 v59, 0xbfb8aa3b, v41
	v_exp_f32_e32 v59, v59
	v_pk_mul_f32 v[68:69], v[70:71], v[68:69]
	v_add_f32_e32 v55, 1.0, v55
	v_rcp_f32_e32 v70, v55
	v_add_f32_e32 v55, 1.0, v59
	v_rcp_f32_e32 v71, v55
	v_lshlrev_b32_e32 v60, 16, v61
	v_and_b32_e32 v61, 0xffff0000, v61
	v_pk_mul_f32 v[38:39], v[38:39], v[60:61]
	v_lshlrev_b32_e32 v60, 16, v62
	v_and_b32_e32 v61, 0xffff0000, v62
	v_pk_mul_f32 v[68:69], v[68:69], v[60:61]
	v_lshlrev_b32_e32 v60, 16, v63
	v_and_b32_e32 v61, 0xffff0000, v63
	v_pk_mul_f32 v[40:41], v[70:71], v[40:41]
	v_cvt_pk_bf16_f32 v62, v68, v69
	v_pk_mul_f32 v[40:41], v[40:41], v[60:61]
	v_cvt_pk_bf16_f32 v61, v38, v39
	v_lshlrev_b64 v[38:39], 12, v[56:57]
	v_lshlrev_b32_e32 v56, 16, v34
	v_lshl_add_u64 v[38:39], s[90:91], 0, v[38:39]
	v_and_b32_e32 v57, 0xffff0000, v34
	v_mul_f32_e32 v34, 0xbfb8aa3b, v56
	v_cvt_pk_bf16_f32 v63, v40, v41
	v_lshl_add_u64 v[38:39], v[38:39], 0, s[10:11]
	v_exp_f32_e32 v34, v34
	v_mul_f32_e32 v41, 0xbfb8aa3b, v57
	v_cvt_pk_bf16_f32 v60, v64, v65
	v_lshl_add_u64 v[38:39], v[38:39], 0, v[0:1]
	v_exp_f32_e32 v59, v41
	global_store_dwordx4 v[38:39], v[60:63], off offset:3072 sc1
	ds_read_b128 v[60:63], v58 offset:3456
	v_add_f32_e32 v34, 1.0, v34
	v_rcp_f32_e32 v64, v34
	v_add_f32_e32 v34, 1.0, v59
	v_rcp_f32_e32 v65, v34
	v_lshlrev_b32_e32 v34, 16, v35
	v_and_b32_e32 v35, 0xffff0000, v35
	v_mul_f32_e32 v59, 0xbfb8aa3b, v34
	s_waitcnt lgkmcnt(0)
	v_lshlrev_b32_e32 v40, 16, v60
	v_and_b32_e32 v41, 0xffff0000, v60
	v_exp_f32_e32 v59, v59
	v_mul_f32_e32 v60, 0xbfb8aa3b, v35
	v_exp_f32_e32 v60, v60
	v_pk_mul_f32 v[56:57], v[64:65], v[56:57]
	v_add_f32_e32 v59, 1.0, v59
	v_rcp_f32_e32 v64, v59
	v_add_f32_e32 v59, 1.0, v60
	v_rcp_f32_e32 v65, v59
	v_lshlrev_b32_e32 v60, 16, v36
	v_pk_mul_f32 v[40:41], v[56:57], v[40:41]
	v_lshlrev_b32_e32 v56, 16, v61
	v_and_b32_e32 v57, 0xffff0000, v61
	v_pk_mul_f32 v[34:35], v[64:65], v[34:35]
	v_and_b32_e32 v61, 0xffff0000, v36
	v_mul_f32_e32 v36, 0xbfb8aa3b, v60
	v_pk_mul_f32 v[34:35], v[34:35], v[56:57]
	v_exp_f32_e32 v36, v36
	v_mul_f32_e32 v57, 0xbfb8aa3b, v61
	v_exp_f32_e32 v59, v57
	v_lshlrev_b32_e32 v56, 16, v62
	v_add_f32_e32 v36, 1.0, v36
	v_rcp_f32_e32 v64, v36
	v_add_f32_e32 v36, 1.0, v59
	v_rcp_f32_e32 v65, v36
	v_lshlrev_b32_e32 v36, 16, v37
	v_and_b32_e32 v37, 0xffff0000, v37
	v_mul_f32_e32 v59, 0xbfb8aa3b, v36
	v_and_b32_e32 v57, 0xffff0000, v62
	v_exp_f32_e32 v59, v59
	v_mul_f32_e32 v62, 0xbfb8aa3b, v37
	v_exp_f32_e32 v62, v62
	v_pk_mul_f32 v[60:61], v[64:65], v[60:61]
	v_add_f32_e32 v59, 1.0, v59
	v_rcp_f32_e32 v64, v59
	v_add_f32_e32 v59, 1.0, v62
	v_rcp_f32_e32 v65, v59
	v_mov_b32_e32 v55, s0
	v_pk_mul_f32 v[56:57], v[60:61], v[56:57]
	v_lshlrev_b32_e32 v60, 16, v63
	v_and_b32_e32 v61, 0xffff0000, v63
	v_pk_mul_f32 v[36:37], v[64:65], v[36:37]
	v_cvt_pk_bf16_f32 v62, v56, v57
	v_pk_mul_f32 v[36:37], v[36:37], v[60:61]
	v_cvt_pk_bf16_f32 v61, v34, v35
	v_lshlrev_b64 v[34:35], 12, v[54:55]
	v_lshl_add_u64 v[34:35], s[90:91], 0, v[34:35]
	v_lshl_add_u64 v[34:35], v[34:35], 0, s[10:11]
	v_cvt_pk_bf16_f32 v60, v40, v41
	v_cvt_pk_bf16_f32 v63, v36, v37
	v_lshl_add_u64 v[36:37], v[34:35], 0, v[0:1]
	global_store_dwordx4 v[36:37], v[60:63], off offset:3072 sc1
	ds_write2_b64 v197, v[18:19], v[20:21] offset1:2
	v_pk_mul_f32 v[18:19], v[26:27], v[66:67] op_sel_hi:[1,0]
	v_pk_mul_f32 v[20:21], v[28:29], v[66:67] op_sel_hi:[1,0]
	ds_write2_b64 v197, v[2:3], v[4:5] offset0:8 offset1:10
	v_pk_mul_f32 v[2:3], v[10:11], v[66:67] op_sel_hi:[1,0]
	v_pk_mul_f32 v[4:5], v[12:13], v[66:67] op_sel_hi:[1,0]
	v_cvt_pk_bf16_f32 v18, v18, v19
	v_cvt_pk_bf16_f32 v19, v20, v21
	v_pk_mul_f32 v[20:21], v[30:31], v[66:67] op_sel_hi:[1,0]
	v_cvt_pk_bf16_f32 v2, v2, v3
	v_cvt_pk_bf16_f32 v3, v4, v5
	v_pk_mul_f32 v[4:5], v[14:15], v[66:67] op_sel_hi:[1,0]
	v_cvt_pk_bf16_f32 v20, v20, v21
	v_cvt_pk_bf16_f32 v21, v22, v23
	v_cvt_pk_bf16_f32 v4, v4, v5
	v_cvt_pk_bf16_f32 v5, v6, v7
	ds_write2_b64 v197, v[18:19], v[20:21] offset0:4 offset1:6
	ds_write2_b64 v197, v[2:3], v[4:5] offset0:12 offset1:14
	v_lshlrev_b32_e32 v0, 1, v174
	s_waitcnt lgkmcnt(0)
	v_lshl_add_u64 v[2:3], v[42:43], 0, v[0:1]
	v_mov_b32_e32 v10, v216
	v_mov_b32_e32 v11, v217
	v_mov_b32_e32 v12, v218
	v_mov_b32_e32 v13, v219
	v_lshl_add_u64 v[2:3], v[48:49], 0, v[0:1]
	v_mov_b32_e32 v14, v220
	v_mov_b32_e32 v15, v221
	v_mov_b32_e32 v16, v222
	v_mov_b32_e32 v17, v223
	v_lshl_add_u64 v[2:3], v[44:45], 0, v[0:1]
	v_lshl_add_u64 v[4:5], v[46:47], 0, v[0:1]
	ds_read_b128 v[18:21], v58
	v_mov_b32_e32 v6, v224
	v_mov_b32_e32 v7, v225
	v_mov_b32_e32 v8, v226
	v_mov_b32_e32 v9, v227
	s_nop 0
	v_mov_b32_e32 v2, v228
	v_mov_b32_e32 v3, v229
	v_mov_b32_e32 v4, v230
	v_mov_b32_e32 v5, v231
	s_mov_b64 s[0:1], 0xc00
	v_lshl_add_u64 v[48:49], v[34:35], 0, s[0:1]
	s_waitcnt lgkmcnt(0)
	v_lshlrev_b32_e32 v22, 16, v18
	v_and_b32_e32 v23, 0xffff0000, v18
	s_waitcnt vmcnt(4)
	v_lshlrev_b32_e32 v24, 16, v10
	v_and_b32_e32 v25, 0xffff0000, v10
	v_mul_f32_e32 v0, 0xbfb8aa3b, v24
	v_exp_f32_e32 v0, v0
	v_mul_f32_e32 v10, 0xbfb8aa3b, v25
	v_exp_f32_e32 v10, v10
	v_add_f32_e32 v0, 1.0, v0
	v_rcp_f32_e32 v26, v0
	v_add_f32_e32 v0, 1.0, v10
	v_lshlrev_b32_e32 v10, 16, v11
	v_rcp_f32_e32 v27, v0
	v_and_b32_e32 v11, 0xffff0000, v11
	v_mul_f32_e32 v0, 0xbfb8aa3b, v10
	v_exp_f32_e32 v0, v0
	v_mul_f32_e32 v18, 0xbfb8aa3b, v11
	v_exp_f32_e32 v18, v18
	v_pk_mul_f32 v[24:25], v[26:27], v[24:25]
	v_add_f32_e32 v0, 1.0, v0
	v_rcp_f32_e32 v26, v0
	v_add_f32_e32 v0, 1.0, v18
	v_rcp_f32_e32 v27, v0
	v_pk_mul_f32 v[22:23], v[24:25], v[22:23]
	v_lshlrev_b32_e32 v24, 16, v12
	v_lshlrev_b32_e32 v18, 16, v19
	v_and_b32_e32 v19, 0xffff0000, v19
	v_pk_mul_f32 v[10:11], v[26:27], v[10:11]
	v_and_b32_e32 v25, 0xffff0000, v12
	v_mul_f32_e32 v0, 0xbfb8aa3b, v24
	v_pk_mul_f32 v[18:19], v[10:11], v[18:19]
	v_exp_f32_e32 v0, v0
	v_mul_f32_e32 v11, 0xbfb8aa3b, v25
	v_exp_f32_e32 v12, v11
	v_lshlrev_b32_e32 v10, 16, v20
	v_add_f32_e32 v0, 1.0, v0
	v_rcp_f32_e32 v26, v0
	v_add_f32_e32 v0, 1.0, v12
	v_lshlrev_b32_e32 v12, 16, v13
	v_rcp_f32_e32 v27, v0
	v_and_b32_e32 v13, 0xffff0000, v13
	v_mul_f32_e32 v0, 0xbfb8aa3b, v12
	v_and_b32_e32 v11, 0xffff0000, v20
	v_exp_f32_e32 v0, v0
	v_mul_f32_e32 v20, 0xbfb8aa3b, v13
	v_exp_f32_e32 v20, v20
	v_pk_mul_f32 v[24:25], v[26:27], v[24:25]
	v_add_f32_e32 v0, 1.0, v0
	v_rcp_f32_e32 v26, v0
	v_add_f32_e32 v0, 1.0, v20
	v_rcp_f32_e32 v27, v0
	v_pk_mul_f32 v[24:25], v[24:25], v[10:11]
	v_lshlrev_b32_e32 v10, 16, v21
	v_and_b32_e32 v11, 0xffff0000, v21
	v_pk_mul_f32 v[12:13], v[26:27], v[12:13]
	s_nop 0
	v_pk_mul_f32 v[20:21], v[12:13], v[10:11]
	v_cvt_pk_bf16_f32 v10, v22, v23
	v_cvt_pk_bf16_f32 v13, v20, v21
	v_lshlrev_b32_e32 v20, 16, v14
	v_and_b32_e32 v21, 0xffff0000, v14
	v_mul_f32_e32 v0, 0xbfb8aa3b, v20
	v_cvt_pk_bf16_f32 v11, v18, v19
	v_cvt_pk_bf16_f32 v12, v24, v25
	v_exp_f32_e32 v0, v0
	v_mul_f32_e32 v14, 0xbfb8aa3b, v21
	global_store_dwordx4 v[50:51], v[10:13], off offset:3200 sc1
	v_exp_f32_e32 v14, v14
	ds_read_b128 v[10:13], v58 offset:1152
	v_add_f32_e32 v0, 1.0, v0
	v_rcp_f32_e32 v22, v0
	v_add_f32_e32 v0, 1.0, v14
	v_lshlrev_b32_e32 v14, 16, v15
	v_rcp_f32_e32 v23, v0
	v_and_b32_e32 v15, 0xffff0000, v15
	v_mul_f32_e32 v0, 0xbfb8aa3b, v14
	s_waitcnt lgkmcnt(0)
	v_lshlrev_b32_e32 v18, 16, v10
	v_and_b32_e32 v19, 0xffff0000, v10
	v_exp_f32_e32 v0, v0
	v_mul_f32_e32 v10, 0xbfb8aa3b, v15
	v_exp_f32_e32 v10, v10
	v_pk_mul_f32 v[20:21], v[22:23], v[20:21]
	v_add_f32_e32 v0, 1.0, v0
	v_rcp_f32_e32 v22, v0
	v_add_f32_e32 v0, 1.0, v10
	v_rcp_f32_e32 v23, v0
	v_pk_mul_f32 v[18:19], v[20:21], v[18:19]
	v_lshlrev_b32_e32 v20, 16, v16
	v_lshlrev_b32_e32 v10, 16, v11
	v_and_b32_e32 v11, 0xffff0000, v11
	v_pk_mul_f32 v[14:15], v[22:23], v[14:15]
	v_and_b32_e32 v21, 0xffff0000, v16
	v_mul_f32_e32 v0, 0xbfb8aa3b, v20
	v_pk_mul_f32 v[14:15], v[14:15], v[10:11]
	v_exp_f32_e32 v0, v0
	v_mul_f32_e32 v11, 0xbfb8aa3b, v21
	v_exp_f32_e32 v16, v11
	v_lshlrev_b32_e32 v10, 16, v12
	v_add_f32_e32 v0, 1.0, v0
	v_rcp_f32_e32 v22, v0
	v_add_f32_e32 v0, 1.0, v16
	v_lshlrev_b32_e32 v16, 16, v17
	v_rcp_f32_e32 v23, v0
	v_and_b32_e32 v17, 0xffff0000, v17
	v_mul_f32_e32 v0, 0xbfb8aa3b, v16
	v_and_b32_e32 v11, 0xffff0000, v12
	v_exp_f32_e32 v0, v0
	v_mul_f32_e32 v12, 0xbfb8aa3b, v17
	v_exp_f32_e32 v12, v12
	v_pk_mul_f32 v[20:21], v[22:23], v[20:21]
	v_add_f32_e32 v0, 1.0, v0
	v_rcp_f32_e32 v22, v0
	v_add_f32_e32 v0, 1.0, v12
	v_rcp_f32_e32 v23, v0
	v_pk_mul_f32 v[20:21], v[20:21], v[10:11]
	v_lshlrev_b32_e32 v10, 16, v13
	v_and_b32_e32 v11, 0xffff0000, v13
	v_pk_mul_f32 v[12:13], v[22:23], v[16:17]
	s_nop 0
	v_pk_mul_f32 v[16:17], v[12:13], v[10:11]
	v_cvt_pk_bf16_f32 v10, v18, v19
	v_cvt_pk_bf16_f32 v13, v16, v17
	v_lshlrev_b32_e32 v16, 16, v6
	v_and_b32_e32 v17, 0xffff0000, v6
	v_mul_f32_e32 v0, 0xbfb8aa3b, v16
	v_cvt_pk_bf16_f32 v11, v14, v15
	v_cvt_pk_bf16_f32 v12, v20, v21
	v_exp_f32_e32 v0, v0
	v_mul_f32_e32 v6, 0xbfb8aa3b, v17
	global_store_dwordx4 v[52:53], v[10:13], off offset:3200 sc1
	v_exp_f32_e32 v6, v6
	ds_read_b128 v[10:13], v58 offset:2304
	v_add_f32_e32 v0, 1.0, v0
	v_rcp_f32_e32 v18, v0
	v_add_f32_e32 v0, 1.0, v6
	v_lshlrev_b32_e32 v6, 16, v7
	v_rcp_f32_e32 v19, v0
	v_and_b32_e32 v7, 0xffff0000, v7
	v_mul_f32_e32 v0, 0xbfb8aa3b, v6
	s_waitcnt lgkmcnt(0)
	v_lshlrev_b32_e32 v14, 16, v10
	v_and_b32_e32 v15, 0xffff0000, v10
	v_exp_f32_e32 v0, v0
	v_mul_f32_e32 v10, 0xbfb8aa3b, v7
	v_exp_f32_e32 v10, v10
	v_pk_mul_f32 v[16:17], v[18:19], v[16:17]
	v_add_f32_e32 v0, 1.0, v0
	v_rcp_f32_e32 v18, v0
	v_add_f32_e32 v0, 1.0, v10
	v_rcp_f32_e32 v19, v0
	v_pk_mul_f32 v[14:15], v[16:17], v[14:15]
	v_lshlrev_b32_e32 v16, 16, v8
	v_lshlrev_b32_e32 v10, 16, v11
	v_and_b32_e32 v11, 0xffff0000, v11
	v_pk_mul_f32 v[6:7], v[18:19], v[6:7]
	v_and_b32_e32 v17, 0xffff0000, v8
	v_mul_f32_e32 v0, 0xbfb8aa3b, v16
	v_pk_mul_f32 v[10:11], v[6:7], v[10:11]
	v_exp_f32_e32 v0, v0
	v_mul_f32_e32 v7, 0xbfb8aa3b, v17
	v_exp_f32_e32 v8, v7
	v_lshlrev_b32_e32 v6, 16, v12
	v_add_f32_e32 v0, 1.0, v0
	v_rcp_f32_e32 v18, v0
	v_add_f32_e32 v0, 1.0, v8
	v_lshlrev_b32_e32 v8, 16, v9
	v_rcp_f32_e32 v19, v0
	v_and_b32_e32 v9, 0xffff0000, v9
	v_mul_f32_e32 v0, 0xbfb8aa3b, v8
	v_and_b32_e32 v7, 0xffff0000, v12
	v_exp_f32_e32 v0, v0
	v_mul_f32_e32 v12, 0xbfb8aa3b, v9
	v_exp_f32_e32 v12, v12
	v_pk_mul_f32 v[16:17], v[18:19], v[16:17]
	v_add_f32_e32 v0, 1.0, v0
	v_rcp_f32_e32 v18, v0
	v_add_f32_e32 v0, 1.0, v12
	v_rcp_f32_e32 v19, v0
	v_pk_mul_f32 v[16:17], v[16:17], v[6:7]
	v_lshlrev_b32_e32 v6, 16, v13
	v_and_b32_e32 v7, 0xffff0000, v13
	v_pk_mul_f32 v[8:9], v[18:19], v[8:9]
	s_nop 0
	v_pk_mul_f32 v[12:13], v[8:9], v[6:7]
	v_cvt_pk_bf16_f32 v6, v14, v15
	v_cvt_pk_bf16_f32 v9, v12, v13
	v_lshlrev_b32_e32 v12, 16, v2
	v_and_b32_e32 v13, 0xffff0000, v2
	v_mul_f32_e32 v0, 0xbfb8aa3b, v12
	v_cvt_pk_bf16_f32 v7, v10, v11
	v_cvt_pk_bf16_f32 v8, v16, v17
	v_exp_f32_e32 v0, v0
	v_mul_f32_e32 v2, 0xbfb8aa3b, v13
	global_store_dwordx4 v[38:39], v[6:9], off offset:3200 sc1
	v_exp_f32_e32 v2, v2
	ds_read_b128 v[6:9], v58 offset:3456
	v_add_f32_e32 v0, 1.0, v0
	v_rcp_f32_e32 v14, v0
	v_add_f32_e32 v0, 1.0, v2
	v_lshlrev_b32_e32 v2, 16, v3
	v_rcp_f32_e32 v15, v0
	v_and_b32_e32 v3, 0xffff0000, v3
	v_mul_f32_e32 v0, 0xbfb8aa3b, v2
	s_waitcnt lgkmcnt(0)
	v_lshlrev_b32_e32 v10, 16, v6
	v_and_b32_e32 v11, 0xffff0000, v6
	v_exp_f32_e32 v0, v0
	v_mul_f32_e32 v6, 0xbfb8aa3b, v3
	v_exp_f32_e32 v6, v6
	v_pk_mul_f32 v[12:13], v[14:15], v[12:13]
	v_add_f32_e32 v0, 1.0, v0
	v_rcp_f32_e32 v14, v0
	v_add_f32_e32 v0, 1.0, v6
	v_rcp_f32_e32 v15, v0
	v_pk_mul_f32 v[10:11], v[12:13], v[10:11]
	v_lshlrev_b32_e32 v12, 16, v4
	v_lshlrev_b32_e32 v6, 16, v7
	v_and_b32_e32 v7, 0xffff0000, v7
	v_pk_mul_f32 v[2:3], v[14:15], v[2:3]
	v_and_b32_e32 v13, 0xffff0000, v4
	v_mul_f32_e32 v0, 0xbfb8aa3b, v12
	v_pk_mul_f32 v[6:7], v[2:3], v[6:7]
	v_exp_f32_e32 v0, v0
	v_mul_f32_e32 v3, 0xbfb8aa3b, v13
	v_exp_f32_e32 v4, v3
	v_lshlrev_b32_e32 v2, 16, v8
	v_add_f32_e32 v0, 1.0, v0
	v_rcp_f32_e32 v14, v0
	v_add_f32_e32 v0, 1.0, v4
	v_lshlrev_b32_e32 v4, 16, v5
	v_rcp_f32_e32 v15, v0
	v_and_b32_e32 v5, 0xffff0000, v5
	v_mul_f32_e32 v0, 0xbfb8aa3b, v4
	v_and_b32_e32 v3, 0xffff0000, v8
	v_exp_f32_e32 v0, v0
	v_mul_f32_e32 v8, 0xbfb8aa3b, v5
	v_exp_f32_e32 v8, v8
	v_pk_mul_f32 v[12:13], v[14:15], v[12:13]
	v_add_f32_e32 v0, 1.0, v0
	v_rcp_f32_e32 v14, v0
	v_add_f32_e32 v0, 1.0, v8
	v_rcp_f32_e32 v15, v0
	v_pk_mul_f32 v[12:13], v[12:13], v[2:3]
	v_lshlrev_b32_e32 v2, 16, v9
	v_and_b32_e32 v3, 0xffff0000, v9
	v_pk_mul_f32 v[4:5], v[14:15], v[4:5]
	s_nop 0
	v_pk_mul_f32 v[8:9], v[4:5], v[2:3]
	v_cvt_pk_bf16_f32 v2, v10, v11
	v_cvt_pk_bf16_f32 v3, v6, v7
	v_cvt_pk_bf16_f32 v4, v12, v13
	v_cvt_pk_bf16_f32 v5, v8, v9
	s_cbranch_execnz .Ltail_nc

.LBB0_623:
	s_waitcnt lgkmcnt(0)
	v_add_f32_e32 v0, v128, v4
	v_rcp_f32_e32 v14, v0
	v_add_u32_e32 v80, v175, v188
	s_ashr_i32 s21, s20, 31
	s_lshl_b32 s0, s17, 7
	v_pk_mul_f32 v[2:3], v[64:65], v[14:15] op_sel_hi:[1,0]
	v_pk_mul_f32 v[4:5], v[66:67], v[14:15] op_sel_hi:[1,0]
	v_cvt_pk_bf16_f32 v2, v2, v3
	v_cvt_pk_bf16_f32 v3, v4, v5
	v_pk_mul_f32 v[4:5], v[68:69], v[14:15] op_sel_hi:[1,0]
	v_pk_mul_f32 v[6:7], v[70:71], v[14:15] op_sel_hi:[1,0]
	v_cvt_pk_bf16_f32 v4, v4, v5
	v_cvt_pk_bf16_f32 v5, v6, v7
	ds_write2_b64 v80, v[2:3], v[4:5] offset1:2
	v_pk_mul_f32 v[2:3], v[72:73], v[14:15] op_sel_hi:[1,0]
	v_pk_mul_f32 v[4:5], v[74:75], v[14:15] op_sel_hi:[1,0]
	s_lshl_b64 s[10:11], s[20:21], 11
	v_readlane_b32 s1, v254, 3
	v_cvt_pk_bf16_f32 v2, v2, v3
	v_cvt_pk_bf16_f32 v3, v4, v5
	v_pk_mul_f32 v[4:5], v[76:77], v[14:15] op_sel_hi:[1,0]
	v_pk_mul_f32 v[6:7], v[78:79], v[14:15] op_sel_hi:[1,0]
	s_add_u32 s1, s10, s1
	v_cvt_pk_bf16_f32 v4, v4, v5
	v_cvt_pk_bf16_f32 v5, v6, v7
	s_addc_u32 s11, s11, 0
	s_lshl_b32 s10, s16, 6
	ds_write2_b64 v80, v[2:3], v[4:5] offset0:4 offset1:6
	v_pk_mul_f32 v[2:3], v[48:49], v[14:15] op_sel_hi:[1,0]
	v_pk_mul_f32 v[4:5], v[50:51], v[14:15] op_sel_hi:[1,0]
	s_add_u32 s10, s1, s10
	v_cvt_pk_bf16_f32 v2, v2, v3
	v_cvt_pk_bf16_f32 v3, v4, v5
	v_pk_mul_f32 v[4:5], v[52:53], v[14:15] op_sel_hi:[1,0]
	v_pk_mul_f32 v[6:7], v[54:55], v[14:15] op_sel_hi:[1,0]
	s_addc_u32 s11, s11, 0
	s_ashr_i32 s1, s0, 31
	v_cvt_pk_bf16_f32 v4, v4, v5
	v_cvt_pk_bf16_f32 v5, v6, v7
	ds_write2_b64 v80, v[2:3], v[4:5] offset0:8 offset1:10
	v_pk_mul_f32 v[2:3], v[56:57], v[14:15] op_sel_hi:[1,0]
	v_pk_mul_f32 v[4:5], v[58:59], v[14:15] op_sel_hi:[1,0]
	s_lshl_b64 s[12:13], s[0:1], 1
	v_cvt_pk_bf16_f32 v2, v2, v3
	v_cvt_pk_bf16_f32 v3, v4, v5
	v_pk_mul_f32 v[4:5], v[60:61], v[14:15] op_sel_hi:[1,0]
	v_pk_mul_f32 v[6:7], v[62:63], v[14:15] op_sel_hi:[1,0]
	s_add_u32 s0, s96, s12
	v_cvt_pk_bf16_f32 v4, v4, v5
	v_cvt_pk_bf16_f32 v5, v6, v7
	s_addc_u32 s1, s97, s13
	ds_write2_b64 v80, v[2:3], v[4:5] offset0:12 offset1:14
	v_or_b32_e32 v68, s10, v164
	v_mov_b64_e32 v[2:3], s[0:1]
	v_mad_u64_u32 v[4:5], s[0:1], v68, s43, v[2:3]
	v_mad_i32_i24 v5, s11, v211, v5
	s_mov_b64 s[14:15], 0x1200
	v_lshl_add_u64 v[56:57], v[4:5], 0, s[14:15]
	v_lshlrev_b32_e32 v0, 1, v166
	s_waitcnt lgkmcnt(0)
	v_lshl_add_u64 v[4:5], v[56:57], 0, v[0:1]
	global_load_dwordx4 v[48:51], v[4:5], off
	v_or_b32_e32 v66, s10, v168
	v_mad_u64_u32 v[4:5], s[0:1], v66, s43, v[2:3]
	v_mad_i32_i24 v5, s11, v211, v5
	v_lshl_add_u64 v[58:59], v[4:5], 0, s[14:15]
	v_lshl_add_u64 v[4:5], v[58:59], 0, v[0:1]
	global_load_dwordx4 v[10:13], v[4:5], off
	v_add_u32_e32 v15, v185, v186
	ds_read_b128 v[52:55], v15
	v_lshl_add_u64 v[64:65], s[10:11], 0, v[176:177]
	v_mad_u64_u32 v[4:5], s[0:1], v64, s43, v[2:3]
	v_mad_i32_i24 v5, v65, s43, v5
	s_waitcnt lgkmcnt(0)
	v_lshlrev_b32_e32 v70, 16, v52
	v_and_b32_e32 v71, 0xffff0000, v52
	v_lshl_add_u64 v[60:61], v[4:5], 0, s[14:15]
	v_lshl_add_u64 v[4:5], v[60:61], 0, v[0:1]
	global_load_dwordx4 v[6:9], v[4:5], off
	v_lshlrev_b32_e32 v52, 16, v53
	v_and_b32_e32 v53, 0xffff0000, v53
	v_mov_b32_e32 v69, s11
	v_lshl_add_u64 v[4:5], s[10:11], 0, v[178:179]
	v_mad_u64_u32 v[2:3], s[0:1], v4, s43, v[2:3]
	v_mad_i32_i24 v3, v5, s43, v3
	v_lshl_add_u64 v[62:63], v[2:3], 0, s[14:15]
	v_lshl_add_u64 v[2:3], v[62:63], 0, v[0:1]
	global_load_dwordx4 v[2:5], v[2:3], off
	v_lshlrev_b32_e32 v232, 1, v174
	v_mov_b32_e32 v233, 0
	v_lshl_add_u64 v[234:235], v[56:57], 0, v[232:233]
	global_load_dwordx4 v[216:219], v[234:235], off
	v_lshl_add_u64 v[234:235], v[58:59], 0, v[232:233]
	global_load_dwordx4 v[220:223], v[234:235], off
	v_lshl_add_u64 v[234:235], v[60:61], 0, v[232:233]
	global_load_dwordx4 v[224:227], v[234:235], off
	v_lshl_add_u64 v[234:235], v[62:63], 0, v[232:233]
	global_load_dwordx4 v[228:231], v[234:235], off
	v_mov_b32_e32 v67, s11
	s_waitcnt vmcnt(0)
	v_mov_b32_e32 v147, v99
	v_mov_b32_e32 v146, v98
	v_mov_b32_e32 v145, v97
	v_mov_b32_e32 v144, v96
	v_mov_b32_e32 v143, v103
	v_mov_b32_e32 v142, v102
	v_mov_b32_e32 v141, v101
	v_mov_b32_e32 v140, v100
	v_mov_b32_e32 v139, v107
	v_mov_b32_e32 v138, v106
	v_mov_b32_e32 v137, v105
	v_mov_b32_e32 v136, v104
	v_mov_b32_e32 v135, v111
	v_mov_b32_e32 v134, v110
	v_mov_b32_e32 v133, v109
	v_mov_b32_e32 v132, v108
	v_mov_b32_e32 v131, v115
	v_mov_b32_e32 v130, v114
	v_mov_b32_e32 v129, v113
	v_mov_b32_e32 v128, v112
	v_mov_b32_e32 v93, v119
	v_mov_b32_e32 v92, v118
	v_mov_b32_e32 v91, v117
	v_mov_b32_e32 v90, v116
	v_mov_b32_e32 v89, v123
	v_mov_b32_e32 v88, v122
	v_mov_b32_e32 v87, v121
	v_mov_b32_e32 v86, v120
	v_mov_b32_e32 v85, v127
	v_mov_b32_e32 v84, v126
	v_mov_b32_e32 v83, v125
	v_mov_b32_e32 v82, v124
	s_mov_b32 s59, s64
	s_mov_b32 s63, s55
	s_mov_b32 s19, s54
	s_mov_b32 s71, s60
	s_mov_b32 s53, s70
	s_mov_b32 s65, s57
	s_mov_b32 s69, s52
	s_mov_b32 s67, s51
	s_mov_b32 s50, s68
	s_mov_b32 s98, s61
	v_mov_b32_e32 v183, v171
	s_mov_b32 s21, s56
	v_mov_b32_e32 v94, v182
	s_mov_b64 s[26:27], s[4:5]
	v_lshlrev_b32_e32 v72, 16, v48
	v_and_b32_e32 v73, 0xffff0000, v48
	v_mul_f32_e32 v48, 0xbfb8aa3b, v72
	v_exp_f32_e32 v48, v48
	s_nop 0
	v_add_f32_e32 v48, 1.0, v48
	v_rcp_f32_e32 v74, v48
	v_mul_f32_e32 v48, 0xbfb8aa3b, v73
	v_exp_f32_e32 v48, v48
	s_nop 0
	v_add_f32_e32 v48, 1.0, v48
	v_rcp_f32_e32 v75, v48
	v_lshlrev_b32_e32 v48, 16, v49
	v_and_b32_e32 v49, 0xffff0000, v49
	v_pk_mul_f32 v[72:73], v[74:75], v[72:73]
	s_nop 0
	v_pk_mul_f32 v[70:71], v[72:73], v[70:71]
	v_mul_f32_e32 v72, 0xbfb8aa3b, v48
	v_mul_f32_e32 v73, 0xbfb8aa3b, v49
	v_exp_f32_e32 v72, v72
	v_exp_f32_e32 v73, v73
	v_add_f32_e32 v72, 1.0, v72
	v_add_f32_e32 v73, 1.0, v73
	v_rcp_f32_e32 v72, v72
	v_rcp_f32_e32 v73, v73
	s_nop 0
	v_pk_mul_f32 v[48:49], v[72:73], v[48:49]
	v_lshlrev_b32_e32 v72, 16, v50
	v_and_b32_e32 v73, 0xffff0000, v50
	v_mul_f32_e32 v50, 0xbfb8aa3b, v72
	v_exp_f32_e32 v50, v50
	v_pk_mul_f32 v[48:49], v[48:49], v[52:53]
	v_lshlrev_b32_e32 v52, 16, v54
	v_and_b32_e32 v53, 0xffff0000, v54
	v_add_f32_e32 v50, 1.0, v50
	v_rcp_f32_e32 v74, v50
	v_mul_f32_e32 v50, 0xbfb8aa3b, v73
	v_exp_f32_e32 v50, v50
	s_nop 0
	v_add_f32_e32 v50, 1.0, v50
	v_rcp_f32_e32 v75, v50
	v_lshlrev_b32_e32 v50, 16, v51
	v_and_b32_e32 v51, 0xffff0000, v51
	v_mul_f32_e32 v54, 0xbfb8aa3b, v50
	v_pk_mul_f32 v[72:73], v[74:75], v[72:73]
	v_exp_f32_e32 v54, v54
	v_pk_mul_f32 v[72:73], v[72:73], v[52:53]
	v_lshlrev_b32_e32 v52, 16, v55
	v_and_b32_e32 v53, 0xffff0000, v55
	v_mul_f32_e32 v55, 0xbfb8aa3b, v51
	v_exp_f32_e32 v55, v55
	v_add_f32_e32 v54, 1.0, v54
	v_rcp_f32_e32 v54, v54
	v_add_f32_e32 v55, 1.0, v55
	v_rcp_f32_e32 v55, v55
	s_nop 0
	v_pk_mul_f32 v[50:51], v[54:55], v[50:51]
	s_nop 0
	v_pk_mul_f32 v[50:51], v[50:51], v[52:53]
	v_cvt_pk_bf16_f32 v53, v48, v49
	v_lshlrev_b64 v[48:49], 12, v[68:69]
	v_lshlrev_b32_e32 v68, 16, v10
	v_and_b32_e32 v69, 0xffff0000, v10
	v_mul_f32_e32 v10, 0xbfb8aa3b, v68
	v_exp_f32_e32 v10, v10
	v_cvt_pk_bf16_f32 v52, v70, v71
	v_lshl_add_u64 v[48:49], s[90:91], 0, v[48:49]
	v_lshl_add_u64 v[48:49], v[48:49], 0, s[12:13]
	v_add_f32_e32 v10, 1.0, v10
	v_rcp_f32_e32 v70, v10
	v_mul_f32_e32 v10, 0xbfb8aa3b, v69
	v_exp_f32_e32 v10, v10
	v_cvt_pk_bf16_f32 v54, v72, v73
	v_cvt_pk_bf16_f32 v55, v50, v51
	v_lshl_add_u64 v[50:51], v[48:49], 0, v[0:1]
	global_store_dwordx4 v[50:51], v[52:55], off sc1
	ds_read_b128 v[52:55], v15 offset:1152
	v_add_f32_e32 v10, 1.0, v10
	v_rcp_f32_e32 v71, v10
	v_lshlrev_b32_e32 v10, 16, v11
	v_and_b32_e32 v11, 0xffff0000, v11
	s_waitcnt lgkmcnt(0)
	v_lshlrev_b32_e32 v48, 16, v52
	v_and_b32_e32 v49, 0xffff0000, v52
	v_pk_mul_f32 v[68:69], v[70:71], v[68:69]
	v_lshlrev_b32_e32 v52, 16, v53
	v_pk_mul_f32 v[48:49], v[68:69], v[48:49]
	v_mul_f32_e32 v68, 0xbfb8aa3b, v10
	v_mul_f32_e32 v69, 0xbfb8aa3b, v11
	v_exp_f32_e32 v68, v68
	v_exp_f32_e32 v69, v69
	v_and_b32_e32 v53, 0xffff0000, v53
	v_add_f32_e32 v68, 1.0, v68
	v_add_f32_e32 v69, 1.0, v69
	v_rcp_f32_e32 v68, v68
	v_rcp_f32_e32 v69, v69
	s_nop 0
	v_pk_mul_f32 v[10:11], v[68:69], v[10:11]
	v_lshlrev_b32_e32 v68, 16, v12
	v_and_b32_e32 v69, 0xffff0000, v12
	v_mul_f32_e32 v12, 0xbfb8aa3b, v68
	v_exp_f32_e32 v12, v12
	v_pk_mul_f32 v[52:53], v[10:11], v[52:53]
	v_lshlrev_b32_e32 v10, 16, v54
	v_and_b32_e32 v11, 0xffff0000, v54
	v_add_f32_e32 v12, 1.0, v12
	v_rcp_f32_e32 v70, v12
	v_mul_f32_e32 v12, 0xbfb8aa3b, v69
	v_exp_f32_e32 v12, v12
	s_nop 0
	v_add_f32_e32 v12, 1.0, v12
	v_rcp_f32_e32 v71, v12
	v_lshlrev_b32_e32 v12, 16, v13
	v_and_b32_e32 v13, 0xffff0000, v13
	v_mul_f32_e32 v54, 0xbfb8aa3b, v12
	v_pk_mul_f32 v[68:69], v[70:71], v[68:69]
	v_exp_f32_e32 v54, v54
	v_pk_mul_f32 v[68:69], v[68:69], v[10:11]
	v_lshlrev_b32_e32 v10, 16, v55
	v_and_b32_e32 v11, 0xffff0000, v55
	v_mul_f32_e32 v55, 0xbfb8aa3b, v13
	v_exp_f32_e32 v55, v55
	v_add_f32_e32 v54, 1.0, v54
	v_rcp_f32_e32 v54, v54
	v_add_f32_e32 v55, 1.0, v55
	v_rcp_f32_e32 v55, v55
	s_nop 0
	v_pk_mul_f32 v[12:13], v[54:55], v[12:13]
	s_nop 0
	v_pk_mul_f32 v[54:55], v[12:13], v[10:11]
	v_cvt_pk_bf16_f32 v10, v48, v49
	v_cvt_pk_bf16_f32 v13, v54, v55
	v_lshlrev_b32_e32 v54, 16, v6
	v_and_b32_e32 v55, 0xffff0000, v6
	v_mul_f32_e32 v6, 0xbfb8aa3b, v54
	v_exp_f32_e32 v6, v6
	v_lshlrev_b64 v[48:49], 12, v[66:67]
	v_lshl_add_u64 v[48:49], s[90:91], 0, v[48:49]
	v_lshl_add_u64 v[48:49], v[48:49], 0, s[12:13]
	v_add_f32_e32 v6, 1.0, v6
	v_rcp_f32_e32 v66, v6
	v_mul_f32_e32 v6, 0xbfb8aa3b, v55
	v_exp_f32_e32 v6, v6
	v_cvt_pk_bf16_f32 v11, v52, v53
	v_cvt_pk_bf16_f32 v12, v68, v69
	v_lshl_add_u64 v[52:53], v[48:49], 0, v[0:1]
	global_store_dwordx4 v[52:53], v[10:13], off sc1
	ds_read_b128 v[10:13], v15 offset:2304
	v_add_f32_e32 v6, 1.0, v6
	v_rcp_f32_e32 v67, v6
	v_lshlrev_b32_e32 v6, 16, v7
	v_and_b32_e32 v7, 0xffff0000, v7
	s_waitcnt lgkmcnt(0)
	v_lshlrev_b32_e32 v48, 16, v10
	v_and_b32_e32 v49, 0xffff0000, v10
	v_pk_mul_f32 v[54:55], v[66:67], v[54:55]
	v_lshlrev_b32_e32 v10, 16, v11
	v_pk_mul_f32 v[48:49], v[54:55], v[48:49]
	v_mul_f32_e32 v54, 0xbfb8aa3b, v6
	v_mul_f32_e32 v55, 0xbfb8aa3b, v7
	v_exp_f32_e32 v54, v54
	v_exp_f32_e32 v55, v55
	v_and_b32_e32 v11, 0xffff0000, v11
	v_add_f32_e32 v54, 1.0, v54
	v_add_f32_e32 v55, 1.0, v55
	v_rcp_f32_e32 v54, v54
	v_rcp_f32_e32 v55, v55
	s_nop 0
	v_pk_mul_f32 v[6:7], v[54:55], v[6:7]
	v_lshlrev_b32_e32 v54, 16, v8
	v_and_b32_e32 v55, 0xffff0000, v8
	v_mul_f32_e32 v8, 0xbfb8aa3b, v54
	v_exp_f32_e32 v8, v8
	v_pk_mul_f32 v[10:11], v[6:7], v[10:11]
	v_lshlrev_b32_e32 v6, 16, v12
	v_and_b32_e32 v7, 0xffff0000, v12
	v_add_f32_e32 v8, 1.0, v8
	v_rcp_f32_e32 v66, v8
	v_mul_f32_e32 v8, 0xbfb8aa3b, v55
	v_exp_f32_e32 v8, v8
	s_nop 0
	v_add_f32_e32 v8, 1.0, v8
	v_rcp_f32_e32 v67, v8
	v_lshlrev_b32_e32 v8, 16, v9
	v_and_b32_e32 v9, 0xffff0000, v9
	v_mul_f32_e32 v12, 0xbfb8aa3b, v8
	v_pk_mul_f32 v[54:55], v[66:67], v[54:55]
	v_exp_f32_e32 v12, v12
	v_pk_mul_f32 v[54:55], v[54:55], v[6:7]
	v_lshlrev_b32_e32 v6, 16, v13
	v_and_b32_e32 v7, 0xffff0000, v13
	v_mul_f32_e32 v13, 0xbfb8aa3b, v9
	v_exp_f32_e32 v13, v13
	v_add_f32_e32 v12, 1.0, v12
	v_rcp_f32_e32 v12, v12
	v_add_f32_e32 v13, 1.0, v13
	v_rcp_f32_e32 v13, v13
	s_nop 0
	v_pk_mul_f32 v[8:9], v[12:13], v[8:9]
	s_nop 0
	v_pk_mul_f32 v[12:13], v[8:9], v[6:7]
	v_cvt_pk_bf16_f32 v6, v48, v49
	v_cvt_pk_bf16_f32 v9, v12, v13
	v_lshlrev_b32_e32 v12, 16, v2
	v_and_b32_e32 v13, 0xffff0000, v2
	v_mul_f32_e32 v2, 0xbfb8aa3b, v12
	v_exp_f32_e32 v2, v2
	v_cvt_pk_bf16_f32 v7, v10, v11
	v_lshlrev_b64 v[10:11], 12, v[64:65]
	v_lshl_add_u64 v[10:11], s[90:91], 0, v[10:11]
	v_add_f32_e32 v2, 1.0, v2
	v_rcp_f32_e32 v48, v2
	v_mul_f32_e32 v2, 0xbfb8aa3b, v13
	v_exp_f32_e32 v2, v2
	v_lshl_add_u64 v[10:11], v[10:11], 0, s[12:13]
	v_cvt_pk_bf16_f32 v8, v54, v55
	v_lshl_add_u64 v[54:55], v[10:11], 0, v[0:1]
	global_store_dwordx4 v[54:55], v[6:9], off sc1
	ds_read_b128 v[6:9], v15 offset:3456
	v_add_f32_e32 v2, 1.0, v2
	v_rcp_f32_e32 v49, v2
	v_lshlrev_b32_e32 v2, 16, v3
	v_and_b32_e32 v3, 0xffff0000, v3
	s_waitcnt lgkmcnt(0)
	v_lshlrev_b32_e32 v10, 16, v6
	v_and_b32_e32 v11, 0xffff0000, v6
	v_pk_mul_f32 v[12:13], v[48:49], v[12:13]
	v_lshlrev_b32_e32 v6, 16, v7
	v_pk_mul_f32 v[10:11], v[12:13], v[10:11]
	v_mul_f32_e32 v12, 0xbfb8aa3b, v2
	v_mul_f32_e32 v13, 0xbfb8aa3b, v3
	v_exp_f32_e32 v12, v12
	v_exp_f32_e32 v13, v13
	v_and_b32_e32 v7, 0xffff0000, v7
	v_add_f32_e32 v12, 1.0, v12
	v_add_f32_e32 v13, 1.0, v13
	v_rcp_f32_e32 v12, v12
	v_rcp_f32_e32 v13, v13
	s_nop 0
	v_pk_mul_f32 v[2:3], v[12:13], v[2:3]
	v_lshlrev_b32_e32 v12, 16, v4
	v_and_b32_e32 v13, 0xffff0000, v4
	v_mul_f32_e32 v4, 0xbfb8aa3b, v12
	v_exp_f32_e32 v4, v4
	v_pk_mul_f32 v[6:7], v[2:3], v[6:7]
	v_lshlrev_b32_e32 v2, 16, v8
	v_and_b32_e32 v3, 0xffff0000, v8
	v_add_f32_e32 v4, 1.0, v4
	v_rcp_f32_e32 v48, v4
	v_mul_f32_e32 v4, 0xbfb8aa3b, v13
	v_exp_f32_e32 v4, v4
	s_nop 0
	v_add_f32_e32 v4, 1.0, v4
	v_rcp_f32_e32 v49, v4
	v_lshlrev_b32_e32 v4, 16, v5
	v_and_b32_e32 v5, 0xffff0000, v5
	v_mul_f32_e32 v8, 0xbfb8aa3b, v4
	v_pk_mul_f32 v[12:13], v[48:49], v[12:13]
	v_exp_f32_e32 v8, v8
	v_pk_mul_f32 v[12:13], v[12:13], v[2:3]
	v_lshlrev_b32_e32 v2, 16, v9
	v_and_b32_e32 v3, 0xffff0000, v9
	v_mul_f32_e32 v9, 0xbfb8aa3b, v5
	v_exp_f32_e32 v9, v9
	v_add_f32_e32 v8, 1.0, v8
	v_rcp_f32_e32 v8, v8
	v_lshl_add_u64 v[48:49], s[10:11], 0, v[180:181]
	v_add_f32_e32 v9, 1.0, v9
	v_rcp_f32_e32 v9, v9
	s_nop 0
	v_pk_mul_f32 v[4:5], v[8:9], v[4:5]
	s_nop 0
	v_pk_mul_f32 v[8:9], v[4:5], v[2:3]
	v_cvt_pk_bf16_f32 v3, v6, v7
	v_lshlrev_b64 v[6:7], 12, v[48:49]
	v_lshl_add_u64 v[6:7], s[90:91], 0, v[6:7]
	v_lshl_add_u64 v[48:49], v[6:7], 0, s[12:13]
	v_cvt_pk_bf16_f32 v2, v10, v11
	v_cvt_pk_bf16_f32 v4, v12, v13
	v_cvt_pk_bf16_f32 v5, v8, v9
	v_lshl_add_u64 v[6:7], v[48:49], 0, v[0:1]
	global_store_dwordx4 v[6:7], v[2:5], off sc1
	v_pk_mul_f32 v[6:7], v[38:39], v[14:15] op_sel_hi:[1,0]
	v_lshlrev_b32_e32 v0, 1, v174
	v_pk_mul_f32 v[2:3], v[32:33], v[14:15] op_sel_hi:[1,0]
	v_pk_mul_f32 v[4:5], v[34:35], v[14:15] op_sel_hi:[1,0]
	v_cvt_pk_bf16_f32 v2, v2, v3
	v_cvt_pk_bf16_f32 v3, v4, v5
	v_pk_mul_f32 v[4:5], v[36:37], v[14:15] op_sel_hi:[1,0]
	s_mov_b64 s[12:13], s[86:87]
	v_cvt_pk_bf16_f32 v4, v4, v5
	v_cvt_pk_bf16_f32 v5, v6, v7
	ds_write2_b64 v80, v[2:3], v[4:5] offset1:2
	v_pk_mul_f32 v[2:3], v[40:41], v[14:15] op_sel_hi:[1,0]
	v_pk_mul_f32 v[4:5], v[42:43], v[14:15] op_sel_hi:[1,0]
	v_cvt_pk_bf16_f32 v2, v2, v3
	v_cvt_pk_bf16_f32 v3, v4, v5
	v_pk_mul_f32 v[4:5], v[44:45], v[14:15] op_sel_hi:[1,0]
	v_pk_mul_f32 v[6:7], v[46:47], v[14:15] op_sel_hi:[1,0]
	v_cvt_pk_bf16_f32 v4, v4, v5
	v_cvt_pk_bf16_f32 v5, v6, v7
	ds_write2_b64 v80, v[2:3], v[4:5] offset0:4 offset1:6
	v_pk_mul_f32 v[2:3], v[16:17], v[14:15] op_sel_hi:[1,0]
	v_pk_mul_f32 v[4:5], v[18:19], v[14:15] op_sel_hi:[1,0]
	v_cvt_pk_bf16_f32 v2, v2, v3
	v_cvt_pk_bf16_f32 v3, v4, v5
	v_pk_mul_f32 v[4:5], v[20:21], v[14:15] op_sel_hi:[1,0]
	v_pk_mul_f32 v[6:7], v[22:23], v[14:15] op_sel_hi:[1,0]
	v_cvt_pk_bf16_f32 v4, v4, v5
	v_cvt_pk_bf16_f32 v5, v6, v7
	ds_write2_b64 v80, v[2:3], v[4:5] offset0:8 offset1:10
	v_pk_mul_f32 v[2:3], v[24:25], v[14:15] op_sel_hi:[1,0]
	v_pk_mul_f32 v[4:5], v[26:27], v[14:15] op_sel_hi:[1,0]
	v_cvt_pk_bf16_f32 v2, v2, v3
	v_cvt_pk_bf16_f32 v3, v4, v5
	v_pk_mul_f32 v[4:5], v[28:29], v[14:15] op_sel_hi:[1,0]
	v_pk_mul_f32 v[6:7], v[30:31], v[14:15] op_sel_hi:[1,0]
	v_cvt_pk_bf16_f32 v4, v4, v5
	v_cvt_pk_bf16_f32 v5, v6, v7
	ds_write2_b64 v80, v[2:3], v[4:5] offset0:12 offset1:14
	s_waitcnt lgkmcnt(0)
	v_lshl_add_u64 v[2:3], v[56:57], 0, v[0:1]
	v_mov_b32_e32 v16, v216
	v_mov_b32_e32 v17, v217
	v_mov_b32_e32 v18, v218
	v_mov_b32_e32 v19, v219
	v_lshl_add_u64 v[2:3], v[58:59], 0, v[0:1]
	v_mov_b32_e32 v10, v220
	v_mov_b32_e32 v11, v221
	v_mov_b32_e32 v12, v222
	v_mov_b32_e32 v13, v223
	v_lshl_add_u64 v[2:3], v[60:61], 0, v[0:1]
	v_mov_b32_e32 v6, v224
	v_mov_b32_e32 v7, v225
	v_mov_b32_e32 v8, v226
	v_mov_b32_e32 v9, v227
	v_lshl_add_u64 v[2:3], v[62:63], 0, v[0:1]
	ds_read_b128 v[20:23], v15
	v_mov_b32_e32 v2, v228
	v_mov_b32_e32 v3, v229
	v_mov_b32_e32 v4, v230
	v_mov_b32_e32 v5, v231
	s_waitcnt lgkmcnt(0)
	v_lshlrev_b32_e32 v24, 16, v20
	v_and_b32_e32 v25, 0xffff0000, v20
	v_lshlrev_b32_e32 v20, 16, v21
	v_and_b32_e32 v21, 0xffff0000, v21
	s_waitcnt vmcnt(4)
	v_lshlrev_b32_e32 v26, 16, v16
	v_mul_f32_e32 v0, 0xbfb8aa3b, v26
	v_exp_f32_e32 v0, v0
	v_and_b32_e32 v27, 0xffff0000, v16
	v_lshlrev_b32_e32 v16, 16, v17
	v_and_b32_e32 v17, 0xffff0000, v17
	v_add_f32_e32 v0, 1.0, v0
	v_rcp_f32_e32 v28, v0
	v_mul_f32_e32 v0, 0xbfb8aa3b, v27
	v_exp_f32_e32 v0, v0
	s_nop 0
	v_add_f32_e32 v0, 1.0, v0
	v_rcp_f32_e32 v29, v0
	v_mul_f32_e32 v0, 0xbfb8aa3b, v16
	v_exp_f32_e32 v0, v0
	v_pk_mul_f32 v[26:27], v[28:29], v[26:27]
	s_nop 0
	v_pk_mul_f32 v[24:25], v[26:27], v[24:25]
	v_add_f32_e32 v0, 1.0, v0
	v_rcp_f32_e32 v26, v0
	v_mul_f32_e32 v0, 0xbfb8aa3b, v17
	v_exp_f32_e32 v0, v0
	s_nop 0
	v_add_f32_e32 v0, 1.0, v0
	v_rcp_f32_e32 v27, v0
	s_nop 0
	v_pk_mul_f32 v[16:17], v[26:27], v[16:17]
	v_lshlrev_b32_e32 v26, 16, v18
	v_mul_f32_e32 v0, 0xbfb8aa3b, v26
	v_exp_f32_e32 v0, v0
	v_and_b32_e32 v27, 0xffff0000, v18
	v_lshlrev_b32_e32 v18, 16, v19
	v_and_b32_e32 v19, 0xffff0000, v19
	v_add_f32_e32 v0, 1.0, v0
	v_rcp_f32_e32 v28, v0
	v_mul_f32_e32 v0, 0xbfb8aa3b, v27
	v_exp_f32_e32 v0, v0
	v_pk_mul_f32 v[20:21], v[16:17], v[20:21]
	v_lshlrev_b32_e32 v16, 16, v22
	v_and_b32_e32 v17, 0xffff0000, v22
	v_add_f32_e32 v0, 1.0, v0
	v_rcp_f32_e32 v29, v0
	v_mul_f32_e32 v0, 0xbfb8aa3b, v18
	v_exp_f32_e32 v0, v0
	v_pk_mul_f32 v[26:27], v[28:29], v[26:27]
	s_nop 0
	v_pk_mul_f32 v[26:27], v[26:27], v[16:17]
	v_add_f32_e32 v0, 1.0, v0
	v_rcp_f32_e32 v22, v0
	v_mul_f32_e32 v0, 0xbfb8aa3b, v19
	v_exp_f32_e32 v0, v0
	v_lshlrev_b32_e32 v16, 16, v23
	v_and_b32_e32 v17, 0xffff0000, v23
	v_add_f32_e32 v0, 1.0, v0
	v_rcp_f32_e32 v23, v0
	s_nop 0
	v_pk_mul_f32 v[18:19], v[22:23], v[18:19]
	s_nop 0
	v_pk_mul_f32 v[22:23], v[18:19], v[16:17]
	v_cvt_pk_bf16_f32 v16, v24, v25
	v_cvt_pk_bf16_f32 v19, v22, v23
	v_lshlrev_b32_e32 v22, 16, v10
	v_mul_f32_e32 v0, 0xbfb8aa3b, v22
	v_exp_f32_e32 v0, v0
	v_and_b32_e32 v23, 0xffff0000, v10
	v_cvt_pk_bf16_f32 v17, v20, v21
	v_cvt_pk_bf16_f32 v18, v26, v27
	v_add_f32_e32 v0, 1.0, v0
	v_rcp_f32_e32 v24, v0
	v_mul_f32_e32 v0, 0xbfb8aa3b, v23
	v_exp_f32_e32 v0, v0
	global_store_dwordx4 v[50:51], v[16:19], off offset:128 sc1
	v_lshlrev_b32_e32 v10, 16, v11
	ds_read_b128 v[16:19], v15 offset:1152
	v_add_f32_e32 v0, 1.0, v0
	v_rcp_f32_e32 v25, v0
	v_mul_f32_e32 v0, 0xbfb8aa3b, v10
	v_exp_f32_e32 v0, v0
	s_waitcnt lgkmcnt(0)
	v_lshlrev_b32_e32 v20, 16, v16
	v_and_b32_e32 v21, 0xffff0000, v16
	v_pk_mul_f32 v[22:23], v[24:25], v[22:23]
	v_and_b32_e32 v11, 0xffff0000, v11
	v_add_f32_e32 v0, 1.0, v0
	v_pk_mul_f32 v[20:21], v[22:23], v[20:21]
	v_rcp_f32_e32 v22, v0
	v_mul_f32_e32 v0, 0xbfb8aa3b, v11
	v_exp_f32_e32 v0, v0
	v_lshlrev_b32_e32 v16, 16, v17
	v_and_b32_e32 v17, 0xffff0000, v17
	v_add_f32_e32 v0, 1.0, v0
	v_rcp_f32_e32 v23, v0
	s_nop 0
	v_pk_mul_f32 v[10:11], v[22:23], v[10:11]
	v_lshlrev_b32_e32 v22, 16, v12
	v_mul_f32_e32 v0, 0xbfb8aa3b, v22
	v_exp_f32_e32 v0, v0
	v_and_b32_e32 v23, 0xffff0000, v12
	v_lshlrev_b32_e32 v12, 16, v13
	v_and_b32_e32 v13, 0xffff0000, v13
	v_add_f32_e32 v0, 1.0, v0
	v_rcp_f32_e32 v24, v0
	v_mul_f32_e32 v0, 0xbfb8aa3b, v23
	v_exp_f32_e32 v0, v0
	v_pk_mul_f32 v[16:17], v[10:11], v[16:17]
	v_lshlrev_b32_e32 v10, 16, v18
	v_and_b32_e32 v11, 0xffff0000, v18
	v_add_f32_e32 v0, 1.0, v0
	v_rcp_f32_e32 v25, v0
	v_mul_f32_e32 v0, 0xbfb8aa3b, v12
	v_exp_f32_e32 v0, v0
	v_pk_mul_f32 v[22:23], v[24:25], v[22:23]
	s_nop 0
	v_pk_mul_f32 v[22:23], v[22:23], v[10:11]
	v_add_f32_e32 v0, 1.0, v0
	v_rcp_f32_e32 v18, v0
	v_mul_f32_e32 v0, 0xbfb8aa3b, v13
	v_exp_f32_e32 v0, v0
	v_lshlrev_b32_e32 v10, 16, v19
	v_and_b32_e32 v11, 0xffff0000, v19
	v_add_f32_e32 v0, 1.0, v0
	v_rcp_f32_e32 v19, v0
	s_nop 0
	v_pk_mul_f32 v[12:13], v[18:19], v[12:13]
	s_nop 0
	v_pk_mul_f32 v[18:19], v[12:13], v[10:11]
	v_cvt_pk_bf16_f32 v10, v20, v21
	v_cvt_pk_bf16_f32 v13, v18, v19
	v_lshlrev_b32_e32 v18, 16, v6
	v_mul_f32_e32 v0, 0xbfb8aa3b, v18
	v_exp_f32_e32 v0, v0
	v_and_b32_e32 v19, 0xffff0000, v6
	v_cvt_pk_bf16_f32 v11, v16, v17
	v_cvt_pk_bf16_f32 v12, v22, v23
	v_add_f32_e32 v0, 1.0, v0
	v_rcp_f32_e32 v20, v0
	v_mul_f32_e32 v0, 0xbfb8aa3b, v19
	v_exp_f32_e32 v0, v0
	global_store_dwordx4 v[52:53], v[10:13], off offset:128 sc1
	v_lshlrev_b32_e32 v6, 16, v7
	ds_read_b128 v[10:13], v15 offset:2304
	v_add_f32_e32 v0, 1.0, v0
	v_rcp_f32_e32 v21, v0
	v_mul_f32_e32 v0, 0xbfb8aa3b, v6
	v_exp_f32_e32 v0, v0
	s_waitcnt lgkmcnt(0)
	v_lshlrev_b32_e32 v16, 16, v10
	v_and_b32_e32 v17, 0xffff0000, v10
	v_pk_mul_f32 v[18:19], v[20:21], v[18:19]
	v_and_b32_e32 v7, 0xffff0000, v7
	v_add_f32_e32 v0, 1.0, v0
	v_pk_mul_f32 v[16:17], v[18:19], v[16:17]
	v_rcp_f32_e32 v18, v0
	v_mul_f32_e32 v0, 0xbfb8aa3b, v7
	v_exp_f32_e32 v0, v0
	v_lshlrev_b32_e32 v10, 16, v11
	v_and_b32_e32 v11, 0xffff0000, v11
	v_add_f32_e32 v0, 1.0, v0
	v_rcp_f32_e32 v19, v0
	s_nop 0
	v_pk_mul_f32 v[6:7], v[18:19], v[6:7]
	v_lshlrev_b32_e32 v18, 16, v8
	v_mul_f32_e32 v0, 0xbfb8aa3b, v18
	v_exp_f32_e32 v0, v0
	v_and_b32_e32 v19, 0xffff0000, v8
	v_lshlrev_b32_e32 v8, 16, v9
	v_and_b32_e32 v9, 0xffff0000, v9
	v_add_f32_e32 v0, 1.0, v0
	v_rcp_f32_e32 v20, v0
	v_mul_f32_e32 v0, 0xbfb8aa3b, v19
	v_exp_f32_e32 v0, v0
	v_pk_mul_f32 v[10:11], v[6:7], v[10:11]
	v_lshlrev_b32_e32 v6, 16, v12
	v_and_b32_e32 v7, 0xffff0000, v12
	v_add_f32_e32 v0, 1.0, v0
	v_rcp_f32_e32 v21, v0
	v_mul_f32_e32 v0, 0xbfb8aa3b, v8
	v_exp_f32_e32 v0, v0
	v_pk_mul_f32 v[18:19], v[20:21], v[18:19]
	s_nop 0
	v_pk_mul_f32 v[18:19], v[18:19], v[6:7]
	v_add_f32_e32 v0, 1.0, v0
	v_rcp_f32_e32 v12, v0
	v_mul_f32_e32 v0, 0xbfb8aa3b, v9
	v_exp_f32_e32 v0, v0
	v_lshlrev_b32_e32 v6, 16, v13
	v_and_b32_e32 v7, 0xffff0000, v13
	v_add_f32_e32 v0, 1.0, v0
	v_rcp_f32_e32 v13, v0
	s_nop 0
	v_pk_mul_f32 v[8:9], v[12:13], v[8:9]
	s_nop 0
	v_pk_mul_f32 v[12:13], v[8:9], v[6:7]
	v_cvt_pk_bf16_f32 v6, v16, v17
	v_cvt_pk_bf16_f32 v9, v12, v13
	v_lshlrev_b32_e32 v12, 16, v2
	v_mul_f32_e32 v0, 0xbfb8aa3b, v12
	v_exp_f32_e32 v0, v0
	v_and_b32_e32 v13, 0xffff0000, v2
	v_cvt_pk_bf16_f32 v7, v10, v11
	v_cvt_pk_bf16_f32 v8, v18, v19
	v_add_f32_e32 v0, 1.0, v0
	v_rcp_f32_e32 v14, v0
	v_mul_f32_e32 v0, 0xbfb8aa3b, v13
	v_exp_f32_e32 v0, v0
	global_store_dwordx4 v[54:55], v[6:9], off offset:128 sc1
	v_lshlrev_b32_e32 v2, 16, v3
	ds_read_b128 v[6:9], v15 offset:3456
	v_add_f32_e32 v0, 1.0, v0
	v_rcp_f32_e32 v15, v0
	v_mul_f32_e32 v0, 0xbfb8aa3b, v2
	v_exp_f32_e32 v0, v0
	s_waitcnt lgkmcnt(0)
	v_lshlrev_b32_e32 v10, 16, v6
	v_and_b32_e32 v11, 0xffff0000, v6
	v_pk_mul_f32 v[12:13], v[14:15], v[12:13]
	v_and_b32_e32 v3, 0xffff0000, v3
	v_add_f32_e32 v0, 1.0, v0
	v_pk_mul_f32 v[10:11], v[12:13], v[10:11]
	v_rcp_f32_e32 v12, v0
	v_mul_f32_e32 v0, 0xbfb8aa3b, v3
	v_exp_f32_e32 v0, v0
	v_lshlrev_b32_e32 v6, 16, v7
	v_and_b32_e32 v7, 0xffff0000, v7
	v_add_f32_e32 v0, 1.0, v0
	v_rcp_f32_e32 v13, v0
	s_nop 0
	v_pk_mul_f32 v[2:3], v[12:13], v[2:3]
	v_lshlrev_b32_e32 v12, 16, v4
	v_mul_f32_e32 v0, 0xbfb8aa3b, v12
	v_exp_f32_e32 v0, v0
	v_and_b32_e32 v13, 0xffff0000, v4
	v_lshlrev_b32_e32 v4, 16, v5
	v_and_b32_e32 v5, 0xffff0000, v5
	v_add_f32_e32 v0, 1.0, v0
	v_rcp_f32_e32 v14, v0
	v_mul_f32_e32 v0, 0xbfb8aa3b, v13
	v_exp_f32_e32 v0, v0
	v_pk_mul_f32 v[6:7], v[2:3], v[6:7]
	v_lshlrev_b32_e32 v2, 16, v8
	v_and_b32_e32 v3, 0xffff0000, v8
	v_add_f32_e32 v0, 1.0, v0
	v_rcp_f32_e32 v15, v0
	v_mul_f32_e32 v0, 0xbfb8aa3b, v4
	v_exp_f32_e32 v0, v0
	v_pk_mul_f32 v[12:13], v[14:15], v[12:13]
	s_nop 0
	v_pk_mul_f32 v[12:13], v[12:13], v[2:3]
	v_add_f32_e32 v0, 1.0, v0
	v_rcp_f32_e32 v8, v0
	v_mul_f32_e32 v0, 0xbfb8aa3b, v5
	v_exp_f32_e32 v0, v0
	v_lshlrev_b32_e32 v2, 16, v9
	v_and_b32_e32 v3, 0xffff0000, v9
	v_add_f32_e32 v0, 1.0, v0
	v_rcp_f32_e32 v9, v0
	s_nop 0
	v_pk_mul_f32 v[4:5], v[8:9], v[4:5]
	s_nop 0
	v_pk_mul_f32 v[8:9], v[4:5], v[2:3]
	v_cvt_pk_bf16_f32 v2, v10, v11
	v_cvt_pk_bf16_f32 v3, v6, v7
	v_cvt_pk_bf16_f32 v4, v12, v13
	v_cvt_pk_bf16_f32 v5, v8, v9
.LBB0_624:
	v_lshlrev_b32_e32 v0, 1, v166
	s_cmp_lt_i32 s7, 0
	v_lshl_add_u64 v[6:7], v[48:49], 0, v[0:1]
	s_cselect_b64 s[4:5], -1, 0
	s_waitcnt vmcnt(7) lgkmcnt(0)
	v_mov_b32_e32 v99, v147
	v_mov_b32_e32 v98, v146
	v_mov_b32_e32 v97, v145
	v_mov_b32_e32 v96, v144
	v_mov_b32_e32 v103, v143
	v_mov_b32_e32 v102, v142
	v_mov_b32_e32 v101, v141
	v_mov_b32_e32 v100, v140
	v_mov_b32_e32 v107, v139
	v_mov_b32_e32 v106, v138
	v_mov_b32_e32 v105, v137
	v_mov_b32_e32 v104, v136
	v_mov_b32_e32 v111, v135
	v_mov_b32_e32 v110, v134
	v_mov_b32_e32 v109, v133
	v_mov_b32_e32 v108, v132
	v_mov_b32_e32 v115, v131
	v_mov_b32_e32 v114, v130
	v_mov_b32_e32 v113, v129
	v_mov_b32_e32 v112, v128
	v_mov_b32_e32 v119, v93
	v_mov_b32_e32 v118, v92
	v_mov_b32_e32 v117, v91
	v_mov_b32_e32 v116, v90
	v_mov_b32_e32 v123, v89
	v_mov_b32_e32 v122, v88
	v_mov_b32_e32 v121, v87
	v_mov_b32_e32 v120, v86
	v_mov_b32_e32 v127, v85
	v_mov_b32_e32 v126, v84
	v_mov_b32_e32 v125, v83
	v_mov_b32_e32 v124, v82
	global_store_dwordx4 v[6:7], v[2:5], off offset:128 sc1
	s_branch .LBB0_348

.LBB0_680:
	s_or_b64 exec, exec, s[0:1]
	s_ashr_i32 s14, s11, 3
	s_lshl_b32 s16, s14, 7
	s_ashr_i32 s11, s10, 31
	s_ashr_i32 s15, s14, 31
	s_ashr_i32 s17, s16, 31
	s_lshl_b64 s[10:11], s[10:11], 11
	s_add_i32 s52, s52, s31
	s_add_u32 s1, s10, s52
	s_addc_u32 s0, s11, 0
	s_lshl_b64 s[86:87], s[16:17], 1
	s_add_u32 s10, s12, s86
	s_addc_u32 s11, s13, s87
	v_or_b32_e32 v196, s1, v124
	v_mov_b64_e32 v[34:35], s[10:11]
	v_mad_u64_u32 v[36:37], s[10:11], v196, s43, v[34:35]
	v_lshl_add_u64 v[42:43], v[134:135], 0, s[86:87]
	v_mad_i32_i24 v37, s0, v211, v37
	s_mov_b64 s[16:17], 0x2a00
	v_lshl_add_u64 v[142:143], v[36:37], 0, s[16:17]
	v_mov_b32_e32 v137, v1
	v_mad_u64_u32 v[146:147], s[10:11], v196, s94, v[42:43]
	s_waitcnt lgkmcnt(0)
	v_lshl_add_u64 v[38:39], v[132:133], 0, s[86:87]
	v_lshl_add_u64 v[36:37], v[142:143], 0, v[136:137]
	v_mad_i32_i24 v147, s0, v214, v147
	global_load_dwordx4 v[70:73], v[36:37], off
	global_load_dwordx4 v[78:81], v[146:147], off
	v_mad_u64_u32 v[144:145], s[10:11], v196, s94, v[38:39]
	v_mad_u64_u32 v[36:37], s[10:11], v196, 24, s[4:5]
	v_mad_i32_i24 v37, s0, 24, v37
	s_lshl_b64 s[10:11], s[14:15], 2
	v_lshl_add_u64 v[156:157], v[36:37], 0, s[10:11]
	v_add_co_u32_e32 v158, vcc, s47, v156
	global_load_dword v0, v[156:157], off
	s_nop 0
	v_addc_co_u32_e32 v159, vcc, 0, v157, vcc
	global_load_dword v200, v[158:159], off
	v_mad_i32_i24 v145, s0, v214, v145
	global_load_dwordx4 v[74:77], v[144:145], off
	v_or_b32_e32 v194, s1, v126
	v_mad_u64_u32 v[36:37], s[14:15], v194, s43, v[34:35]
	v_mad_i32_i24 v37, s0, v211, v37
	v_lshl_add_u64 v[160:161], v[36:37], 0, s[16:17]
	v_lshl_add_u64 v[36:37], v[160:161], 0, v[136:137]
	global_load_dwordx4 v[58:61], v[36:37], off
	v_mad_u64_u32 v[36:37], s[14:15], v194, 24, s[4:5]
	v_mad_i32_i24 v37, s0, 24, v37
	v_lshl_add_u64 v[166:167], v[36:37], 0, s[10:11]
	v_add_co_u32_e32 v168, vcc, s47, v166
	v_or_b32_e32 v192, s1, v128
	s_nop 0
	v_addc_co_u32_e32 v169, vcc, 0, v167, vcc
	v_mad_u64_u32 v[36:37], s[14:15], v192, s43, v[34:35]
	global_load_dword v225, v[166:167], off
	global_load_dword v226, v[168:169], off
	v_mad_i32_i24 v37, s0, v211, v37
	v_lshl_add_u64 v[170:171], v[36:37], 0, s[16:17]
	v_lshl_add_u64 v[36:37], v[170:171], 0, v[136:137]
	global_load_dwordx4 v[46:49], v[36:37], off
	v_mad_u64_u32 v[36:37], s[14:15], v192, 24, s[4:5]
	v_mad_i32_i24 v37, s0, 24, v37
	v_or_b32_e32 v190, s1, v130
	v_lshl_add_u64 v[176:177], v[36:37], 0, s[10:11]
	v_mad_u64_u32 v[114:115], s[14:15], v190, 24, s[4:5]
	v_add_co_u32_e32 v178, vcc, s47, v176
	v_mad_u64_u32 v[34:35], s[14:15], v190, s43, v[34:35]
	v_mad_i32_i24 v115, s0, 24, v115
	v_addc_co_u32_e32 v179, vcc, 0, v177, vcc
	v_mad_i32_i24 v35, s0, v211, v35
	v_lshl_add_u64 v[186:187], v[114:115], 0, s[10:11]
	v_mad_u64_u32 v[162:163], s[14:15], v194, s94, v[38:39]
	v_mad_u64_u32 v[164:165], s[14:15], v194, s94, v[42:43]
	v_mad_u64_u32 v[172:173], s[14:15], v192, s94, v[38:39]
	v_mad_u64_u32 v[174:175], s[14:15], v192, s94, v[42:43]
	v_lshl_add_u64 v[180:181], v[34:35], 0, s[16:17]
	v_mad_u64_u32 v[182:183], s[14:15], v190, s94, v[38:39]
	v_mad_u64_u32 v[184:185], s[14:15], v190, s94, v[42:43]
	v_add_co_u32_e32 v188, vcc, s47, v186
	v_mad_i32_i24 v163, s0, v214, v163
	v_mad_i32_i24 v165, s0, v214, v165
	v_mad_i32_i24 v173, s0, v214, v173
	v_mad_i32_i24 v175, s0, v214, v175
	v_lshl_add_u64 v[34:35], v[180:181], 0, v[136:137]
	v_mad_i32_i24 v183, s0, v214, v183
	v_mad_i32_i24 v185, s0, v214, v185
	v_addc_co_u32_e32 v189, vcc, 0, v187, vcc
	v_add_u32_e32 v221, v131, v122
	global_load_dwordx4 v[62:65], v[162:163], off
	global_load_dwordx4 v[66:69], v[164:165], off
	global_load_dwordx4 v[50:53], v[172:173], off
	global_load_dwordx4 v[54:57], v[174:175], off
	global_load_dword v223, v[176:177], off
	global_load_dword v224, v[178:179], off
	global_load_dwordx4 v[38:41], v[182:183], off
	global_load_dwordx4 v[42:45], v[184:185], off
	global_load_dword v139, v[186:187], off
	global_load_dword v222, v[188:189], off
	s_waitcnt vmcnt(0) lgkmcnt(0)
	v_lshlrev_b32_e32 v234, 16, v70
	global_load_dwordx4 v[34:37], v[34:35], off
	ds_read_b128 v[114:117], v221
	ds_read_b32 v198, v131 offset:128
	v_and_b32_e32 v235, 0xffff0000, v70
	v_mul_f32_e32 v70, 0xbfb8aa3b, v234
	v_exp_f32_e32 v70, v70
	s_waitcnt lgkmcnt(0)
	v_and_b32_e32 v229, 0xffff0000, v114
	v_max3_f32 v201, v198, v0, v200
	v_sub_f32_e32 v198, v198, v201
	v_sub_f32_e32 v0, v0, v201
	v_exp_f32_e32 v199, v198
	v_exp_f32_e32 v198, v0
	v_sub_f32_e32 v0, v200, v201
	v_exp_f32_e32 v0, v0
	v_add_f32_e32 v70, 1.0, v70
	v_add_f32_e32 v200, v199, v198
	v_rcp_f32_e32 v236, v70
	v_add_f32_e32 v200, v0, v200
	v_rcp_f32_e32 v200, v200
	v_mul_f32_e32 v70, 0xbfb8aa3b, v235
	v_exp_f32_e32 v70, v70
	v_lshlrev_b32_e32 v230, 16, v114
	v_mul_f32_e32 v0, v0, v200
	v_pk_mul_f32 v[202:203], v[198:199], v[200:201] op_sel_hi:[1,0]
	v_lshlrev_b32_e32 v200, 16, v117
	v_and_b32_e32 v201, 0xffff0000, v77
	v_lshlrev_b32_e32 v198, 16, v77
	v_and_b32_e32 v199, 0xffff0000, v117
	v_pk_mul_f32 v[200:201], v[202:203], v[200:201] op_sel:[1,0] op_sel_hi:[0,1]
	v_add_f32_e32 v70, 1.0, v70
	v_pk_fma_f32 v[198:199], v[202:203], v[198:199], v[200:201]
	v_lshlrev_b32_e32 v200, 16, v81
	v_and_b32_e32 v201, 0xffff0000, v81
	v_rcp_f32_e32 v237, v70
	v_lshlrev_b32_e32 v70, 16, v71
	v_pk_fma_f32 v[198:199], v[0:1], v[200:201], v[198:199] op_sel_hi:[0,1,1]
	v_lshlrev_b32_e32 v200, 16, v73
	v_and_b32_e32 v201, 0xffff0000, v73
	v_mul_f32_e32 v73, 0xbfb8aa3b, v70
	v_exp_f32_e32 v73, v73
	v_and_b32_e32 v71, 0xffff0000, v71
	v_and_b32_e32 v231, 0xffff0000, v74
	v_lshlrev_b32_e32 v228, 16, v74
	v_add_f32_e32 v73, 1.0, v73
	v_rcp_f32_e32 v114, v73
	v_mul_f32_e32 v73, 0xbfb8aa3b, v71
	v_exp_f32_e32 v73, v73
	v_pk_mul_f32 v[230:231], v[202:203], v[230:231] op_sel:[1,0] op_sel_hi:[0,1]
	v_pk_fma_f32 v[228:229], v[202:203], v[228:229], v[230:231]
	v_and_b32_e32 v231, 0xffff0000, v115
	v_add_f32_e32 v73, 1.0, v73
	v_lshlrev_b32_e32 v74, 16, v115
	v_rcp_f32_e32 v115, v73
	v_lshlrev_b32_e32 v230, 16, v75
	v_and_b32_e32 v75, 0xffff0000, v75
	v_pk_mul_f32 v[74:75], v[202:203], v[74:75] op_sel:[1,0] op_sel_hi:[0,1]
	v_lshlrev_b32_e32 v232, 16, v78
	v_and_b32_e32 v233, 0xffff0000, v78
	v_lshlrev_b32_e32 v78, 16, v79
	v_and_b32_e32 v79, 0xffff0000, v79
	v_pk_fma_f32 v[74:75], v[202:203], v[230:231], v[74:75]
	v_pk_mul_f32 v[70:71], v[114:115], v[70:71]
	v_pk_fma_f32 v[74:75], v[0:1], v[78:79], v[74:75] op_sel_hi:[0,1,1]
	v_pk_mul_f32 v[70:71], v[70:71], v[74:75]
	v_lshlrev_b32_e32 v74, 16, v76
	v_and_b32_e32 v79, 0xffff0000, v76
	v_lshlrev_b32_e32 v76, 16, v80
	v_and_b32_e32 v77, 0xffff0000, v80
	v_lshlrev_b32_e32 v80, 16, v72
	v_and_b32_e32 v81, 0xffff0000, v72
	v_mul_f32_e32 v72, 0xbfb8aa3b, v80
	v_mul_f32_e32 v73, 0xbfb8aa3b, v81
	v_exp_f32_e32 v72, v72
	v_exp_f32_e32 v73, v73
	v_lshlrev_b32_e32 v78, 16, v116
	v_and_b32_e32 v75, 0xffff0000, v116
	v_pk_mul_f32 v[78:79], v[202:203], v[78:79] op_sel:[1,0] op_sel_hi:[0,1]
	v_pk_fma_f32 v[74:75], v[202:203], v[74:75], v[78:79]
	v_pk_fma_f32 v[228:229], v[0:1], v[232:233], v[228:229] op_sel_hi:[0,1,1]
	v_add_f32_e32 v72, 1.0, v72
	v_add_f32_e32 v73, 1.0, v73
	v_pk_fma_f32 v[74:75], v[0:1], v[76:77], v[74:75] op_sel_hi:[0,1,1]
	v_mul_f32_e32 v0, 0xbfb8aa3b, v200
	v_rcp_f32_e32 v72, v72
	v_rcp_f32_e32 v73, v73
	v_exp_f32_e32 v0, v0
	v_mov_b32_e32 v197, s0
	v_pk_mul_f32 v[234:235], v[236:237], v[234:235]
	v_pk_mul_f32 v[72:73], v[72:73], v[80:81]
	v_add_f32_e32 v0, 1.0, v0
	v_pk_mul_f32 v[74:75], v[72:73], v[74:75]
	v_rcp_f32_e32 v72, v0
	v_mul_f32_e32 v0, 0xbfb8aa3b, v201
	v_exp_f32_e32 v0, v0
	v_pk_mul_f32 v[228:229], v[234:235], v[228:229]
	v_cvt_pk_bf16_f32 v74, v74, v75
	v_add_u32_e32 v78, v217, v122
	v_add_f32_e32 v0, 1.0, v0
	v_rcp_f32_e32 v73, v0
	v_lshlrev_b32_e32 v80, 16, v62
	v_mov_b32_e32 v195, s0
	v_mov_b32_e32 v193, s0
	v_pk_mul_f32 v[72:73], v[72:73], v[200:201]
	v_lshlrev_b32_e32 v200, 16, v58
	v_pk_mul_f32 v[76:77], v[72:73], v[198:199]
	v_cvt_pk_bf16_f32 v73, v70, v71
	v_lshlrev_b64 v[70:71], 12, v[196:197]
	v_lshl_add_u64 v[70:71], s[8:9], 0, v[70:71]
	v_lshl_add_u64 v[70:71], v[70:71], 0, s[86:87]
	v_cvt_pk_bf16_f32 v72, v228, v229
	v_cvt_pk_bf16_f32 v75, v76, v77
	v_lshl_add_u64 v[70:71], v[70:71], 0, v[136:137]
	global_store_dwordx4 v[70:71], v[72:75], off offset:1536 sc1
	ds_read_b128 v[114:117], v78
	ds_read_b32 v0, v217 offset:128
	v_and_b32_e32 v201, 0xffff0000, v58
	v_mul_f32_e32 v58, 0xbfb8aa3b, v200
	v_exp_f32_e32 v58, v58
	s_waitcnt lgkmcnt(0)
	v_and_b32_e32 v81, 0xffff0000, v114
	v_max3_f32 v74, v0, v225, v226
	v_sub_f32_e32 v0, v0, v74
	v_exp_f32_e32 v73, v0
	v_sub_f32_e32 v0, v225, v74
	v_exp_f32_e32 v72, v0
	v_sub_f32_e32 v0, v226, v74
	v_exp_f32_e32 v0, v0
	v_add_f32_e32 v58, 1.0, v58
	v_add_f32_e32 v74, v73, v72
	v_rcp_f32_e32 v202, v58
	v_add_f32_e32 v74, v0, v74
	v_rcp_f32_e32 v74, v74
	v_mul_f32_e32 v58, 0xbfb8aa3b, v201
	v_exp_f32_e32 v58, v58
	v_lshlrev_b32_e32 v196, 16, v114
	v_mul_f32_e32 v0, v0, v74
	v_pk_mul_f32 v[76:77], v[72:73], v[74:75] op_sel_hi:[1,0]
	v_lshlrev_b32_e32 v74, 16, v117
	v_and_b32_e32 v75, 0xffff0000, v65
	v_lshlrev_b32_e32 v72, 16, v65
	v_and_b32_e32 v73, 0xffff0000, v117
	v_pk_mul_f32 v[74:75], v[76:77], v[74:75] op_sel:[1,0] op_sel_hi:[0,1]
	v_add_f32_e32 v58, 1.0, v58
	v_pk_fma_f32 v[72:73], v[76:77], v[72:73], v[74:75]
	v_lshlrev_b32_e32 v74, 16, v69
	v_and_b32_e32 v75, 0xffff0000, v69
	v_rcp_f32_e32 v203, v58
	v_lshlrev_b32_e32 v58, 16, v59
	v_pk_fma_f32 v[72:73], v[0:1], v[74:75], v[72:73] op_sel_hi:[0,1,1]
	v_lshlrev_b32_e32 v74, 16, v61
	v_and_b32_e32 v75, 0xffff0000, v61
	v_mul_f32_e32 v61, 0xbfb8aa3b, v58
	v_exp_f32_e32 v61, v61
	v_and_b32_e32 v59, 0xffff0000, v59
	v_and_b32_e32 v197, 0xffff0000, v62
	v_pk_mul_f32 v[196:197], v[76:77], v[196:197] op_sel:[1,0] op_sel_hi:[0,1]
	v_add_f32_e32 v61, 1.0, v61
	v_rcp_f32_e32 v114, v61
	v_mul_f32_e32 v61, 0xbfb8aa3b, v59
	v_exp_f32_e32 v61, v61
	v_pk_fma_f32 v[80:81], v[76:77], v[80:81], v[196:197]
	v_and_b32_e32 v197, 0xffff0000, v115
	v_lshlrev_b32_e32 v62, 16, v115
	v_add_f32_e32 v61, 1.0, v61
	v_rcp_f32_e32 v115, v61
	v_lshlrev_b32_e32 v196, 16, v63
	v_and_b32_e32 v63, 0xffff0000, v63
	v_pk_mul_f32 v[62:63], v[76:77], v[62:63] op_sel:[1,0] op_sel_hi:[0,1]
	v_lshlrev_b32_e32 v198, 16, v66
	v_and_b32_e32 v199, 0xffff0000, v66
	v_lshlrev_b32_e32 v66, 16, v67
	v_and_b32_e32 v67, 0xffff0000, v67
	v_pk_fma_f32 v[62:63], v[76:77], v[196:197], v[62:63]
	v_pk_mul_f32 v[58:59], v[114:115], v[58:59]
	v_pk_fma_f32 v[62:63], v[0:1], v[66:67], v[62:63] op_sel_hi:[0,1,1]
	v_pk_mul_f32 v[58:59], v[58:59], v[62:63]
	v_lshlrev_b32_e32 v62, 16, v64
	v_and_b32_e32 v67, 0xffff0000, v64
	v_lshlrev_b32_e32 v64, 16, v68
	v_and_b32_e32 v65, 0xffff0000, v68
	v_lshlrev_b32_e32 v68, 16, v60
	v_and_b32_e32 v69, 0xffff0000, v60
	v_mul_f32_e32 v60, 0xbfb8aa3b, v68
	v_mul_f32_e32 v61, 0xbfb8aa3b, v69
	v_exp_f32_e32 v60, v60
	v_exp_f32_e32 v61, v61
	v_lshlrev_b32_e32 v66, 16, v116
	v_and_b32_e32 v63, 0xffff0000, v116
	v_pk_mul_f32 v[66:67], v[76:77], v[66:67] op_sel:[1,0] op_sel_hi:[0,1]
	v_pk_fma_f32 v[62:63], v[76:77], v[62:63], v[66:67]
	v_pk_fma_f32 v[80:81], v[0:1], v[198:199], v[80:81] op_sel_hi:[0,1,1]
	v_add_f32_e32 v60, 1.0, v60
	v_add_f32_e32 v61, 1.0, v61
	v_pk_fma_f32 v[62:63], v[0:1], v[64:65], v[62:63] op_sel_hi:[0,1,1]
	v_mul_f32_e32 v0, 0xbfb8aa3b, v74
	v_rcp_f32_e32 v60, v60
	v_rcp_f32_e32 v61, v61
	v_exp_f32_e32 v0, v0
	v_pk_mul_f32 v[200:201], v[202:203], v[200:201]
	v_add_u32_e32 v66, v218, v122
	v_pk_mul_f32 v[60:61], v[60:61], v[68:69]
	v_add_f32_e32 v0, 1.0, v0
	v_pk_mul_f32 v[62:63], v[60:61], v[62:63]
	v_rcp_f32_e32 v60, v0
	v_mul_f32_e32 v0, 0xbfb8aa3b, v75
	v_exp_f32_e32 v0, v0
	v_pk_mul_f32 v[80:81], v[200:201], v[80:81]
	v_cvt_pk_bf16_f32 v62, v62, v63
	v_lshlrev_b32_e32 v114, 16, v46
	v_add_f32_e32 v0, 1.0, v0
	v_rcp_f32_e32 v61, v0
	v_and_b32_e32 v115, 0xffff0000, v46
	v_mul_f32_e32 v46, 0xbfb8aa3b, v114
	v_exp_f32_e32 v46, v46
	v_pk_mul_f32 v[60:61], v[60:61], v[74:75]
	v_and_b32_e32 v77, 0xffff0000, v50
	v_pk_mul_f32 v[64:65], v[60:61], v[72:73]
	v_cvt_pk_bf16_f32 v61, v58, v59
	v_lshlrev_b64 v[58:59], 12, v[194:195]
	v_lshl_add_u64 v[58:59], s[8:9], 0, v[58:59]
	v_lshl_add_u64 v[58:59], v[58:59], 0, s[86:87]
	v_cvt_pk_bf16_f32 v60, v80, v81
	v_cvt_pk_bf16_f32 v63, v64, v65
	v_lshl_add_u64 v[58:59], v[58:59], 0, v[136:137]
	global_store_dwordx4 v[58:59], v[60:63], off offset:1536 sc1
	ds_read_b128 v[72:75], v66
	ds_read_b32 v0, v218 offset:128
	v_add_f32_e32 v46, 1.0, v46
	v_rcp_f32_e32 v116, v46
	v_mul_f32_e32 v46, 0xbfb8aa3b, v115
	v_exp_f32_e32 v46, v46
	s_waitcnt lgkmcnt(0)
	v_max3_f32 v62, v0, v223, v224
	v_sub_f32_e32 v0, v0, v62
	v_exp_f32_e32 v61, v0
	v_sub_f32_e32 v0, v223, v62
	v_exp_f32_e32 v60, v0
	v_sub_f32_e32 v0, v224, v62
	v_exp_f32_e32 v0, v0
	v_add_f32_e32 v46, 1.0, v46
	v_add_f32_e32 v62, v61, v60
	v_rcp_f32_e32 v117, v46
	v_add_f32_e32 v62, v0, v62
	v_rcp_f32_e32 v62, v62
	v_lshlrev_b32_e32 v46, 16, v47
	v_and_b32_e32 v47, 0xffff0000, v47
	v_and_b32_e32 v69, 0xffff0000, v72
	v_mul_f32_e32 v0, v0, v62
	v_pk_mul_f32 v[64:65], v[60:61], v[62:63] op_sel_hi:[1,0]
	v_lshlrev_b32_e32 v62, 16, v75
	v_and_b32_e32 v63, 0xffff0000, v53
	v_lshlrev_b32_e32 v60, 16, v53
	v_and_b32_e32 v61, 0xffff0000, v75
	v_pk_mul_f32 v[62:63], v[64:65], v[62:63] op_sel:[1,0] op_sel_hi:[0,1]
	v_pk_fma_f32 v[60:61], v[64:65], v[60:61], v[62:63]
	v_lshlrev_b32_e32 v62, 16, v57
	v_and_b32_e32 v63, 0xffff0000, v57
	v_pk_fma_f32 v[60:61], v[0:1], v[62:63], v[60:61] op_sel_hi:[0,1,1]
	v_lshlrev_b32_e32 v62, 16, v49
	v_and_b32_e32 v63, 0xffff0000, v49
	v_mul_f32_e32 v49, 0xbfb8aa3b, v46
	v_exp_f32_e32 v49, v49
	v_lshlrev_b32_e32 v76, 16, v72
	v_lshlrev_b32_e32 v68, 16, v50
	v_pk_mul_f32 v[76:77], v[64:65], v[76:77] op_sel:[1,0] op_sel_hi:[0,1]
	v_add_f32_e32 v49, 1.0, v49
	v_rcp_f32_e32 v72, v49
	v_mul_f32_e32 v49, 0xbfb8aa3b, v47
	v_exp_f32_e32 v49, v49
	v_pk_fma_f32 v[68:69], v[64:65], v[68:69], v[76:77]
	v_and_b32_e32 v77, 0xffff0000, v73
	v_lshlrev_b32_e32 v50, 16, v73
	v_add_f32_e32 v49, 1.0, v49
	v_rcp_f32_e32 v73, v49
	v_lshlrev_b32_e32 v76, 16, v51
	v_and_b32_e32 v51, 0xffff0000, v51
	v_pk_mul_f32 v[50:51], v[64:65], v[50:51] op_sel:[1,0] op_sel_hi:[0,1]
	v_lshlrev_b32_e32 v80, 16, v54
	v_and_b32_e32 v81, 0xffff0000, v54
	v_lshlrev_b32_e32 v54, 16, v55
	v_and_b32_e32 v55, 0xffff0000, v55
	v_pk_fma_f32 v[50:51], v[64:65], v[76:77], v[50:51]
	v_pk_mul_f32 v[46:47], v[72:73], v[46:47]
	v_pk_fma_f32 v[50:51], v[0:1], v[54:55], v[50:51] op_sel_hi:[0,1,1]
	v_pk_mul_f32 v[50:51], v[46:47], v[50:51]
	v_lshlrev_b32_e32 v46, 16, v52
	v_and_b32_e32 v55, 0xffff0000, v52
	v_lshlrev_b32_e32 v52, 16, v56
	v_and_b32_e32 v53, 0xffff0000, v56
	v_lshlrev_b32_e32 v56, 16, v48
	v_and_b32_e32 v57, 0xffff0000, v48
	v_mul_f32_e32 v48, 0xbfb8aa3b, v56
	v_mul_f32_e32 v49, 0xbfb8aa3b, v57
	v_exp_f32_e32 v48, v48
	v_exp_f32_e32 v49, v49
	v_lshlrev_b32_e32 v54, 16, v74
	v_and_b32_e32 v47, 0xffff0000, v74
	v_pk_mul_f32 v[54:55], v[64:65], v[54:55] op_sel:[1,0] op_sel_hi:[0,1]
	v_pk_fma_f32 v[46:47], v[64:65], v[46:47], v[54:55]
	v_pk_fma_f32 v[68:69], v[0:1], v[80:81], v[68:69] op_sel_hi:[0,1,1]
	v_add_f32_e32 v48, 1.0, v48
	v_add_f32_e32 v49, 1.0, v49
	v_pk_fma_f32 v[46:47], v[0:1], v[52:53], v[46:47] op_sel_hi:[0,1,1]
	v_mul_f32_e32 v0, 0xbfb8aa3b, v62
	v_rcp_f32_e32 v48, v48
	v_rcp_f32_e32 v49, v49
	v_exp_f32_e32 v0, v0
	v_pk_mul_f32 v[114:115], v[116:117], v[114:115]
	v_add_u32_e32 v67, v219, v122
	v_pk_mul_f32 v[48:49], v[48:49], v[56:57]
	v_add_f32_e32 v0, 1.0, v0
	v_pk_mul_f32 v[48:49], v[48:49], v[46:47]
	v_rcp_f32_e32 v46, v0
	v_mul_f32_e32 v0, 0xbfb8aa3b, v63
	v_exp_f32_e32 v0, v0
	v_pk_mul_f32 v[68:69], v[114:115], v[68:69]
	v_cvt_pk_bf16_f32 v48, v48, v49
	v_and_b32_e32 v57, 0xffff0000, v38
	v_add_f32_e32 v0, 1.0, v0
	v_rcp_f32_e32 v47, v0
	v_lshlrev_b32_e32 v64, 16, v42
	v_and_b32_e32 v65, 0xffff0000, v42
	v_lshlrev_b32_e32 v42, 16, v43
	v_pk_mul_f32 v[46:47], v[46:47], v[62:63]
	v_and_b32_e32 v43, 0xffff0000, v43
	v_pk_mul_f32 v[52:53], v[46:47], v[60:61]
	v_cvt_pk_bf16_f32 v47, v50, v51
	v_lshlrev_b64 v[50:51], 12, v[192:193]
	v_lshl_add_u64 v[50:51], s[8:9], 0, v[50:51]
	v_lshl_add_u64 v[50:51], v[50:51], 0, s[86:87]
	v_cvt_pk_bf16_f32 v46, v68, v69
	v_cvt_pk_bf16_f32 v49, v52, v53
	v_lshl_add_u64 v[54:55], v[50:51], 0, v[136:137]
	global_store_dwordx4 v[54:55], v[46:49], off offset:1536 sc1
	ds_read_b128 v[60:63], v67
	ds_read_b32 v0, v219 offset:128
	s_waitcnt vmcnt(0)
	v_lshlrev_b32_e32 v68, 16, v34
	v_and_b32_e32 v69, 0xffff0000, v34
	v_mul_f32_e32 v34, 0xbfb8aa3b, v68
	v_exp_f32_e32 v34, v34
	s_waitcnt lgkmcnt(0)
	v_max3_f32 v48, v0, v139, v222
	v_sub_f32_e32 v0, v0, v48
	v_exp_f32_e32 v47, v0
	v_sub_f32_e32 v0, v139, v48
	v_exp_f32_e32 v46, v0
	v_sub_f32_e32 v0, v222, v48
	v_exp_f32_e32 v0, v0
	v_add_f32_e32 v34, 1.0, v34
	v_add_f32_e32 v48, v47, v46
	v_rcp_f32_e32 v72, v34
	v_add_f32_e32 v48, v0, v48
	v_rcp_f32_e32 v48, v48
	v_mul_f32_e32 v34, 0xbfb8aa3b, v69
	v_exp_f32_e32 v34, v34
	v_and_b32_e32 v53, 0xffff0000, v60
	v_mul_f32_e32 v0, v0, v48
	v_pk_mul_f32 v[50:51], v[46:47], v[48:49] op_sel_hi:[1,0]
	v_lshlrev_b32_e32 v48, 16, v63
	v_and_b32_e32 v49, 0xffff0000, v41
	v_lshlrev_b32_e32 v46, 16, v41
	v_and_b32_e32 v47, 0xffff0000, v63
	v_pk_mul_f32 v[48:49], v[50:51], v[48:49] op_sel:[1,0] op_sel_hi:[0,1]
	v_add_f32_e32 v34, 1.0, v34
	v_pk_fma_f32 v[46:47], v[50:51], v[46:47], v[48:49]
	v_lshlrev_b32_e32 v48, 16, v45
	v_and_b32_e32 v49, 0xffff0000, v45
	v_rcp_f32_e32 v73, v34
	v_lshlrev_b32_e32 v34, 16, v35
	v_pk_fma_f32 v[46:47], v[0:1], v[48:49], v[46:47] op_sel_hi:[0,1,1]
	v_lshlrev_b32_e32 v48, 16, v37
	v_and_b32_e32 v49, 0xffff0000, v37
	v_mul_f32_e32 v37, 0xbfb8aa3b, v34
	v_exp_f32_e32 v37, v37
	v_and_b32_e32 v35, 0xffff0000, v35
	v_lshlrev_b32_e32 v56, 16, v60
	v_lshlrev_b32_e32 v52, 16, v38
	v_add_f32_e32 v37, 1.0, v37
	v_rcp_f32_e32 v60, v37
	v_mul_f32_e32 v37, 0xbfb8aa3b, v35
	v_exp_f32_e32 v37, v37
	v_pk_mul_f32 v[56:57], v[50:51], v[56:57] op_sel:[1,0] op_sel_hi:[0,1]
	v_pk_fma_f32 v[52:53], v[50:51], v[52:53], v[56:57]
	v_and_b32_e32 v57, 0xffff0000, v61
	v_add_f32_e32 v37, 1.0, v37
	v_lshlrev_b32_e32 v38, 16, v61
	v_rcp_f32_e32 v61, v37
	v_lshlrev_b32_e32 v56, 16, v39
	v_and_b32_e32 v39, 0xffff0000, v39
	v_pk_mul_f32 v[38:39], v[50:51], v[38:39] op_sel:[1,0] op_sel_hi:[0,1]
	v_pk_fma_f32 v[38:39], v[50:51], v[56:57], v[38:39]
	v_pk_mul_f32 v[34:35], v[60:61], v[34:35]
	v_pk_fma_f32 v[38:39], v[0:1], v[42:43], v[38:39] op_sel_hi:[0,1,1]
	v_pk_mul_f32 v[38:39], v[34:35], v[38:39]
	v_lshlrev_b32_e32 v34, 16, v40
	v_and_b32_e32 v43, 0xffff0000, v40
	v_lshlrev_b32_e32 v40, 16, v44
	v_and_b32_e32 v41, 0xffff0000, v44
	v_lshlrev_b32_e32 v44, 16, v36
	v_and_b32_e32 v45, 0xffff0000, v36
	v_mul_f32_e32 v36, 0xbfb8aa3b, v44
	v_mul_f32_e32 v37, 0xbfb8aa3b, v45
	v_exp_f32_e32 v36, v36
	v_exp_f32_e32 v37, v37
	v_lshlrev_b32_e32 v42, 16, v62
	v_and_b32_e32 v35, 0xffff0000, v62
	v_pk_mul_f32 v[42:43], v[50:51], v[42:43] op_sel:[1,0] op_sel_hi:[0,1]
	v_pk_fma_f32 v[34:35], v[50:51], v[34:35], v[42:43]
	v_pk_fma_f32 v[52:53], v[0:1], v[64:65], v[52:53] op_sel_hi:[0,1,1]
	v_add_f32_e32 v36, 1.0, v36
	v_add_f32_e32 v37, 1.0, v37
	v_pk_fma_f32 v[34:35], v[0:1], v[40:41], v[34:35] op_sel_hi:[0,1,1]
	v_mul_f32_e32 v0, 0xbfb8aa3b, v48
	v_rcp_f32_e32 v36, v36
	v_rcp_f32_e32 v37, v37
	v_exp_f32_e32 v0, v0
	v_mov_b32_e32 v191, s0
	v_mov_b32_e32 v141, v140
	v_pk_mul_f32 v[36:37], v[36:37], v[44:45]
	v_add_f32_e32 v0, 1.0, v0
	v_pk_mul_f32 v[36:37], v[36:37], v[34:35]
	v_rcp_f32_e32 v34, v0
	v_mul_f32_e32 v0, 0xbfb8aa3b, v49
	v_exp_f32_e32 v0, v0
	v_pk_mul_f32 v[68:69], v[72:73], v[68:69]
	v_pk_mul_f32 v[18:19], v[18:19], v[140:141]
	v_pk_mul_f32 v[20:21], v[20:21], v[140:141]
	v_add_f32_e32 v0, 1.0, v0
	v_rcp_f32_e32 v35, v0
	v_pk_mul_f32 v[2:3], v[2:3], v[140:141]
	v_pk_mul_f32 v[4:5], v[4:5], v[140:141]
	v_pk_mul_f32 v[52:53], v[68:69], v[52:53]
	v_pk_mul_f32 v[34:35], v[34:35], v[48:49]
	v_cvt_pk_bf16_f32 v18, v18, v19
	v_pk_mul_f32 v[40:41], v[34:35], v[46:47]
	v_cvt_pk_bf16_f32 v35, v38, v39
	v_lshlrev_b64 v[38:39], 12, v[190:191]
	v_lshl_add_u64 v[38:39], s[8:9], 0, v[38:39]
	v_lshl_add_u64 v[38:39], v[38:39], 0, s[86:87]
	v_cvt_pk_bf16_f32 v19, v20, v21
	v_pk_mul_f32 v[20:21], v[22:23], v[140:141]
	v_pk_mul_f32 v[22:23], v[24:25], v[140:141]
	v_cvt_pk_bf16_f32 v2, v2, v3
	v_cvt_pk_bf16_f32 v3, v4, v5
	v_pk_mul_f32 v[4:5], v[6:7], v[140:141]
	v_pk_mul_f32 v[6:7], v[8:9], v[140:141]
	v_cvt_pk_bf16_f32 v34, v52, v53
	v_cvt_pk_bf16_f32 v36, v36, v37
	v_cvt_pk_bf16_f32 v37, v40, v41
	v_lshl_add_u64 v[56:57], v[38:39], 0, v[136:137]
	v_cvt_pk_bf16_f32 v20, v20, v21
	v_cvt_pk_bf16_f32 v21, v22, v23
	v_cvt_pk_bf16_f32 v4, v4, v5
	v_cvt_pk_bf16_f32 v5, v6, v7
	global_store_dwordx4 v[56:57], v[34:37], off offset:1536 sc1
	ds_write2_b64 v220, v[18:19], v[20:21] offset1:2
	v_pk_mul_f32 v[18:19], v[26:27], v[140:141]
	v_pk_mul_f32 v[20:21], v[28:29], v[140:141]
	ds_write2_b64 v220, v[2:3], v[4:5] offset0:8 offset1:10
	v_pk_mul_f32 v[2:3], v[10:11], v[140:141]
	v_pk_mul_f32 v[4:5], v[12:13], v[140:141]
	v_cvt_pk_bf16_f32 v18, v18, v19
	v_cvt_pk_bf16_f32 v19, v20, v21
	v_pk_mul_f32 v[20:21], v[30:31], v[140:141]
	v_pk_mul_f32 v[22:23], v[32:33], v[140:141]
	v_cvt_pk_bf16_f32 v2, v2, v3
	v_cvt_pk_bf16_f32 v3, v4, v5
	v_pk_mul_f32 v[4:5], v[14:15], v[140:141]
	v_pk_mul_f32 v[6:7], v[16:17], v[140:141]
	v_cvt_pk_bf16_f32 v20, v20, v21
	v_cvt_pk_bf16_f32 v21, v22, v23
	v_cvt_pk_bf16_f32 v4, v4, v5
	v_cvt_pk_bf16_f32 v5, v6, v7
	ds_write2_b64 v220, v[18:19], v[20:21] offset0:4 offset1:6
	ds_write2_b64 v220, v[2:3], v[4:5] offset0:12 offset1:14
	v_mov_b32_e32 v139, v1
	s_waitcnt lgkmcnt(0)
	v_lshl_add_u64 v[2:3], v[142:143], 0, v[138:139]
	global_load_dwordx4 v[38:41], v[2:3], off
	global_load_dwordx4 v[46:49], v[144:145], off offset:128
	global_load_dwordx4 v[42:45], v[146:147], off offset:128
	global_load_dword v0, v[156:157], off
	global_load_dword v62, v[158:159], off
	v_lshl_add_u64 v[2:3], v[160:161], 0, v[138:139]
	global_load_dwordx4 v[26:29], v[2:3], off
	global_load_dwordx4 v[34:37], v[162:163], off offset:128
	global_load_dwordx4 v[30:33], v[164:165], off offset:128
	global_load_dword v79, v[166:167], off
	global_load_dword v137, v[168:169], off
	v_lshl_add_u64 v[2:3], v[170:171], 0, v[138:139]
	global_load_dwordx4 v[14:17], v[2:3], off
	global_load_dwordx4 v[22:25], v[172:173], off offset:128
	global_load_dwordx4 v[18:21], v[174:175], off offset:128
	global_load_dword v73, v[176:177], off
	global_load_dword v72, v[178:179], off
	v_lshl_add_u64 v[2:3], v[180:181], 0, v[138:139]
	global_load_dwordx4 v[2:5], v[2:3], off
	s_nop 0
	global_load_dwordx4 v[10:13], v[182:183], off offset:128
	global_load_dwordx4 v[6:9], v[184:185], off offset:128
	global_load_dword v69, v[186:187], off
	global_load_dword v68, v[188:189], off
	ds_read_b128 v[50:53], v221
	ds_read_b32 v60, v131 offset:128
	s_andn2_b64 vcc, exec, s[26:27]
	s_waitcnt lgkmcnt(0)
	v_and_b32_e32 v75, 0xffff0000, v50
	v_lshlrev_b32_e32 v76, 16, v50
	s_waitcnt vmcnt(0)
	v_lshlrev_b32_e32 v114, 16, v38
	v_and_b32_e32 v115, 0xffff0000, v38
	v_mul_f32_e32 v38, 0xbfb8aa3b, v114
	v_exp_f32_e32 v38, v38
	v_max3_f32 v63, v60, v0, v62
	v_sub_f32_e32 v60, v60, v63
	v_sub_f32_e32 v0, v0, v63
	v_exp_f32_e32 v61, v60
	v_exp_f32_e32 v60, v0
	v_sub_f32_e32 v0, v62, v63
	v_exp_f32_e32 v0, v0
	v_add_f32_e32 v38, 1.0, v38
	v_add_f32_e32 v62, v61, v60
	v_rcp_f32_e32 v116, v38
	v_add_f32_e32 v62, v0, v62
	v_rcp_f32_e32 v62, v62
	v_mul_f32_e32 v38, 0xbfb8aa3b, v115
	v_exp_f32_e32 v38, v38
	v_and_b32_e32 v77, 0xffff0000, v46
	v_mul_f32_e32 v0, v0, v62
	v_pk_mul_f32 v[64:65], v[60:61], v[62:63] op_sel_hi:[1,0]
	v_lshlrev_b32_e32 v62, 16, v53
	v_and_b32_e32 v63, 0xffff0000, v49
	v_lshlrev_b32_e32 v60, 16, v49
	v_and_b32_e32 v61, 0xffff0000, v53
	v_pk_mul_f32 v[62:63], v[64:65], v[62:63] op_sel:[1,0] op_sel_hi:[0,1]
	v_add_f32_e32 v38, 1.0, v38
	v_pk_fma_f32 v[60:61], v[64:65], v[60:61], v[62:63]
	v_lshlrev_b32_e32 v62, 16, v45
	v_and_b32_e32 v63, 0xffff0000, v45
	v_rcp_f32_e32 v117, v38
	v_lshlrev_b32_e32 v38, 16, v39
	v_pk_fma_f32 v[60:61], v[0:1], v[62:63], v[60:61] op_sel_hi:[0,1,1]
	v_lshlrev_b32_e32 v62, 16, v41
	v_and_b32_e32 v63, 0xffff0000, v41
	v_mul_f32_e32 v41, 0xbfb8aa3b, v38
	v_exp_f32_e32 v41, v41
	v_and_b32_e32 v39, 0xffff0000, v39
	v_lshlrev_b32_e32 v74, 16, v46
	v_pk_mul_f32 v[76:77], v[64:65], v[76:77] op_sel:[1,0] op_sel_hi:[0,1]
	v_add_f32_e32 v41, 1.0, v41
	v_rcp_f32_e32 v50, v41
	v_mul_f32_e32 v41, 0xbfb8aa3b, v39
	v_exp_f32_e32 v41, v41
	v_pk_fma_f32 v[74:75], v[64:65], v[74:75], v[76:77]
	v_and_b32_e32 v77, 0xffff0000, v51
	v_lshlrev_b32_e32 v46, 16, v51
	v_add_f32_e32 v41, 1.0, v41
	v_rcp_f32_e32 v51, v41
	v_lshlrev_b32_e32 v76, 16, v47
	v_and_b32_e32 v47, 0xffff0000, v47
	v_pk_mul_f32 v[46:47], v[64:65], v[46:47] op_sel:[1,0] op_sel_hi:[0,1]
	v_lshlrev_b32_e32 v80, 16, v42
	v_and_b32_e32 v81, 0xffff0000, v42
	v_lshlrev_b32_e32 v42, 16, v43
	v_and_b32_e32 v43, 0xffff0000, v43
	v_pk_fma_f32 v[46:47], v[64:65], v[76:77], v[46:47]
	v_pk_mul_f32 v[38:39], v[50:51], v[38:39]
	v_pk_fma_f32 v[42:43], v[0:1], v[42:43], v[46:47] op_sel_hi:[0,1,1]
	v_pk_mul_f32 v[42:43], v[38:39], v[42:43]
	v_lshlrev_b32_e32 v38, 16, v48
	v_and_b32_e32 v47, 0xffff0000, v48
	v_lshlrev_b32_e32 v48, 16, v44
	v_and_b32_e32 v49, 0xffff0000, v44
	v_lshlrev_b32_e32 v44, 16, v40
	v_and_b32_e32 v45, 0xffff0000, v40
	v_mul_f32_e32 v40, 0xbfb8aa3b, v44
	v_mul_f32_e32 v41, 0xbfb8aa3b, v45
	v_exp_f32_e32 v40, v40
	v_exp_f32_e32 v41, v41
	v_lshlrev_b32_e32 v46, 16, v52
	v_and_b32_e32 v39, 0xffff0000, v52
	v_add_f32_e32 v40, 1.0, v40
	v_add_f32_e32 v41, 1.0, v41
	v_rcp_f32_e32 v40, v40
	v_rcp_f32_e32 v41, v41
	v_pk_fma_f32 v[74:75], v[0:1], v[80:81], v[74:75] op_sel_hi:[0,1,1]
	v_pk_mul_f32 v[114:115], v[116:117], v[114:115]
	v_and_b32_e32 v51, 0xffff0000, v34
	v_pk_mul_f32 v[40:41], v[40:41], v[44:45]
	v_pk_mul_f32 v[44:45], v[64:65], v[46:47] op_sel:[1,0] op_sel_hi:[0,1]
	v_pk_fma_f32 v[38:39], v[64:65], v[38:39], v[44:45]
	v_pk_mul_f32 v[74:75], v[114:115], v[74:75]
	v_pk_fma_f32 v[38:39], v[0:1], v[48:49], v[38:39] op_sel_hi:[0,1,1]
	v_mul_f32_e32 v0, 0xbfb8aa3b, v62
	v_exp_f32_e32 v0, v0
	v_pk_mul_f32 v[40:41], v[40:41], v[38:39]
	v_lshlrev_b32_e32 v48, 16, v34
	v_cvt_pk_bf16_f32 v40, v40, v41
	v_add_f32_e32 v0, 1.0, v0
	v_rcp_f32_e32 v38, v0
	v_mul_f32_e32 v0, 0xbfb8aa3b, v63
	v_exp_f32_e32 v0, v0
	v_lshlrev_b32_e32 v52, 16, v30
	v_and_b32_e32 v53, 0xffff0000, v30
	v_lshlrev_b32_e32 v30, 16, v31
	v_add_f32_e32 v0, 1.0, v0
	v_rcp_f32_e32 v39, v0
	v_and_b32_e32 v31, 0xffff0000, v31
	v_pk_mul_f32 v[38:39], v[38:39], v[62:63]
	s_nop 0
	v_pk_mul_f32 v[44:45], v[38:39], v[60:61]
	v_cvt_pk_bf16_f32 v38, v74, v75
	v_cvt_pk_bf16_f32 v39, v42, v43
	v_cvt_pk_bf16_f32 v41, v44, v45
	global_store_dwordx4 v[70:71], v[38:41], off offset:1664 sc1
	ds_read_b128 v[44:47], v78
	ds_read_b32 v0, v217 offset:128
	v_lshlrev_b32_e32 v60, 16, v26
	v_and_b32_e32 v61, 0xffff0000, v26
	v_mul_f32_e32 v26, 0xbfb8aa3b, v60
	v_exp_f32_e32 v26, v26
	s_waitcnt lgkmcnt(0)
	v_max3_f32 v40, v0, v79, v137
	v_sub_f32_e32 v0, v0, v40
	v_exp_f32_e32 v39, v0
	v_sub_f32_e32 v0, v79, v40
	v_exp_f32_e32 v38, v0
	v_sub_f32_e32 v0, v137, v40
	v_exp_f32_e32 v0, v0
	v_add_f32_e32 v26, 1.0, v26
	v_add_f32_e32 v40, v39, v38
	v_rcp_f32_e32 v62, v26
	v_add_f32_e32 v40, v0, v40
	v_rcp_f32_e32 v40, v40
	v_mul_f32_e32 v26, 0xbfb8aa3b, v61
	v_exp_f32_e32 v26, v26
	v_and_b32_e32 v49, 0xffff0000, v44
	v_mul_f32_e32 v0, v0, v40
	v_pk_mul_f32 v[42:43], v[38:39], v[40:41] op_sel_hi:[1,0]
	v_lshlrev_b32_e32 v40, 16, v47
	v_and_b32_e32 v41, 0xffff0000, v37
	v_lshlrev_b32_e32 v38, 16, v37
	v_and_b32_e32 v39, 0xffff0000, v47
	v_pk_mul_f32 v[40:41], v[42:43], v[40:41] op_sel:[1,0] op_sel_hi:[0,1]
	v_add_f32_e32 v26, 1.0, v26
	v_pk_fma_f32 v[38:39], v[42:43], v[38:39], v[40:41]
	v_lshlrev_b32_e32 v40, 16, v33
	v_and_b32_e32 v41, 0xffff0000, v33
	v_rcp_f32_e32 v63, v26
	v_lshlrev_b32_e32 v26, 16, v27
	v_pk_fma_f32 v[38:39], v[0:1], v[40:41], v[38:39] op_sel_hi:[0,1,1]
	v_lshlrev_b32_e32 v40, 16, v29
	v_and_b32_e32 v41, 0xffff0000, v29
	v_mul_f32_e32 v29, 0xbfb8aa3b, v26
	v_exp_f32_e32 v29, v29
	v_and_b32_e32 v27, 0xffff0000, v27
	v_lshlrev_b32_e32 v50, 16, v44
	v_pk_mul_f32 v[50:51], v[42:43], v[50:51] op_sel:[1,0] op_sel_hi:[0,1]
	v_add_f32_e32 v29, 1.0, v29
	v_rcp_f32_e32 v44, v29
	v_mul_f32_e32 v29, 0xbfb8aa3b, v27
	v_exp_f32_e32 v29, v29
	v_pk_fma_f32 v[48:49], v[42:43], v[48:49], v[50:51]
	v_and_b32_e32 v51, 0xffff0000, v45
	v_lshlrev_b32_e32 v34, 16, v45
	v_add_f32_e32 v29, 1.0, v29
	v_rcp_f32_e32 v45, v29
	v_lshlrev_b32_e32 v50, 16, v35
	v_and_b32_e32 v35, 0xffff0000, v35
	v_pk_mul_f32 v[34:35], v[42:43], v[34:35] op_sel:[1,0] op_sel_hi:[0,1]
	v_pk_fma_f32 v[34:35], v[42:43], v[50:51], v[34:35]
	v_pk_mul_f32 v[26:27], v[44:45], v[26:27]
	v_pk_fma_f32 v[30:31], v[0:1], v[30:31], v[34:35] op_sel_hi:[0,1,1]
	v_pk_mul_f32 v[30:31], v[26:27], v[30:31]
	v_lshlrev_b32_e32 v26, 16, v36
	v_and_b32_e32 v35, 0xffff0000, v36
	v_lshlrev_b32_e32 v36, 16, v32
	v_and_b32_e32 v37, 0xffff0000, v32
	v_lshlrev_b32_e32 v32, 16, v28
	v_and_b32_e32 v33, 0xffff0000, v28
	v_mul_f32_e32 v28, 0xbfb8aa3b, v32
	v_mul_f32_e32 v29, 0xbfb8aa3b, v33
	v_exp_f32_e32 v28, v28
	v_exp_f32_e32 v29, v29
	v_lshlrev_b32_e32 v34, 16, v46
	v_and_b32_e32 v27, 0xffff0000, v46
	v_add_f32_e32 v28, 1.0, v28
	v_add_f32_e32 v29, 1.0, v29
	v_rcp_f32_e32 v28, v28
	v_rcp_f32_e32 v29, v29
	v_pk_fma_f32 v[48:49], v[0:1], v[52:53], v[48:49] op_sel_hi:[0,1,1]
	v_pk_mul_f32 v[60:61], v[62:63], v[60:61]
	v_pk_mul_f32 v[28:29], v[28:29], v[32:33]
	v_pk_mul_f32 v[32:33], v[42:43], v[34:35] op_sel:[1,0] op_sel_hi:[0,1]
	v_pk_fma_f32 v[26:27], v[42:43], v[26:27], v[32:33]
	v_pk_mul_f32 v[48:49], v[60:61], v[48:49]
	v_pk_fma_f32 v[26:27], v[0:1], v[36:37], v[26:27] op_sel_hi:[0,1,1]
	v_mul_f32_e32 v0, 0xbfb8aa3b, v40
	v_exp_f32_e32 v0, v0
	v_pk_mul_f32 v[28:29], v[28:29], v[26:27]
	v_lshlrev_b32_e32 v42, 16, v14
	v_cvt_pk_bf16_f32 v28, v28, v29
	v_add_f32_e32 v0, 1.0, v0
	v_rcp_f32_e32 v26, v0
	v_mul_f32_e32 v0, 0xbfb8aa3b, v41
	v_exp_f32_e32 v0, v0
	v_and_b32_e32 v43, 0xffff0000, v14
	v_mul_f32_e32 v14, 0xbfb8aa3b, v42
	v_exp_f32_e32 v14, v14
	v_add_f32_e32 v0, 1.0, v0
	v_rcp_f32_e32 v27, v0
	v_lshlrev_b32_e32 v36, 16, v22
	v_add_f32_e32 v14, 1.0, v14
	v_rcp_f32_e32 v44, v14
	v_pk_mul_f32 v[26:27], v[26:27], v[40:41]
	v_mul_f32_e32 v14, 0xbfb8aa3b, v43
	v_pk_mul_f32 v[32:33], v[26:27], v[38:39]
	v_cvt_pk_bf16_f32 v26, v48, v49
	v_cvt_pk_bf16_f32 v27, v30, v31
	v_cvt_pk_bf16_f32 v29, v32, v33
	global_store_dwordx4 v[58:59], v[26:29], off offset:1664 sc1
	ds_read_b128 v[32:35], v66
	ds_read_b32 v0, v218 offset:128
	v_exp_f32_e32 v14, v14
	v_and_b32_e32 v39, 0xffff0000, v22
	v_lshlrev_b32_e32 v40, 16, v18
	s_waitcnt lgkmcnt(0)
	v_and_b32_e32 v37, 0xffff0000, v32
	v_max3_f32 v28, v0, v73, v72
	v_sub_f32_e32 v0, v0, v28
	v_exp_f32_e32 v27, v0
	v_sub_f32_e32 v0, v73, v28
	v_exp_f32_e32 v26, v0
	v_sub_f32_e32 v0, v72, v28
	v_exp_f32_e32 v0, v0
	v_add_f32_e32 v14, 1.0, v14
	v_add_f32_e32 v28, v27, v26
	v_rcp_f32_e32 v45, v14
	v_add_f32_e32 v28, v0, v28
	v_rcp_f32_e32 v28, v28
	v_lshlrev_b32_e32 v14, 16, v15
	v_and_b32_e32 v15, 0xffff0000, v15
	v_lshlrev_b32_e32 v38, 16, v32
	v_mul_f32_e32 v0, v0, v28
	v_pk_mul_f32 v[30:31], v[26:27], v[28:29] op_sel_hi:[1,0]
	v_lshlrev_b32_e32 v28, 16, v35
	v_and_b32_e32 v29, 0xffff0000, v25
	v_lshlrev_b32_e32 v26, 16, v25
	v_and_b32_e32 v27, 0xffff0000, v35
	v_pk_mul_f32 v[28:29], v[30:31], v[28:29] op_sel:[1,0] op_sel_hi:[0,1]
	v_pk_fma_f32 v[26:27], v[30:31], v[26:27], v[28:29]
	v_lshlrev_b32_e32 v28, 16, v21
	v_and_b32_e32 v29, 0xffff0000, v21
	v_pk_fma_f32 v[26:27], v[0:1], v[28:29], v[26:27] op_sel_hi:[0,1,1]
	v_lshlrev_b32_e32 v28, 16, v17
	v_and_b32_e32 v29, 0xffff0000, v17
	v_mul_f32_e32 v17, 0xbfb8aa3b, v14
	v_exp_f32_e32 v17, v17
	v_pk_mul_f32 v[38:39], v[30:31], v[38:39] op_sel:[1,0] op_sel_hi:[0,1]
	v_pk_fma_f32 v[36:37], v[30:31], v[36:37], v[38:39]
	v_and_b32_e32 v39, 0xffff0000, v33
	v_add_f32_e32 v17, 1.0, v17
	v_rcp_f32_e32 v32, v17
	v_mul_f32_e32 v17, 0xbfb8aa3b, v15
	v_exp_f32_e32 v17, v17
	v_lshlrev_b32_e32 v22, 16, v33
	v_lshlrev_b32_e32 v38, 16, v23
	v_and_b32_e32 v23, 0xffff0000, v23
	v_add_f32_e32 v17, 1.0, v17
	v_rcp_f32_e32 v33, v17
	v_pk_mul_f32 v[22:23], v[30:31], v[22:23] op_sel:[1,0] op_sel_hi:[0,1]
	v_and_b32_e32 v41, 0xffff0000, v18
	v_lshlrev_b32_e32 v18, 16, v19
	v_and_b32_e32 v19, 0xffff0000, v19
	v_pk_fma_f32 v[22:23], v[30:31], v[38:39], v[22:23]
	v_pk_mul_f32 v[14:15], v[32:33], v[14:15]
	v_pk_fma_f32 v[18:19], v[0:1], v[18:19], v[22:23] op_sel_hi:[0,1,1]
	v_pk_mul_f32 v[18:19], v[14:15], v[18:19]
	v_lshlrev_b32_e32 v14, 16, v24
	v_and_b32_e32 v23, 0xffff0000, v24
	v_lshlrev_b32_e32 v24, 16, v20
	v_and_b32_e32 v25, 0xffff0000, v20
	v_lshlrev_b32_e32 v20, 16, v16
	v_and_b32_e32 v21, 0xffff0000, v16
	v_mul_f32_e32 v16, 0xbfb8aa3b, v20
	v_mul_f32_e32 v17, 0xbfb8aa3b, v21
	v_exp_f32_e32 v16, v16
	v_exp_f32_e32 v17, v17
	v_lshlrev_b32_e32 v22, 16, v34
	v_and_b32_e32 v15, 0xffff0000, v34
	v_add_f32_e32 v16, 1.0, v16
	v_add_f32_e32 v17, 1.0, v17
	v_rcp_f32_e32 v16, v16
	v_rcp_f32_e32 v17, v17
	v_pk_fma_f32 v[36:37], v[0:1], v[40:41], v[36:37] op_sel_hi:[0,1,1]
	v_pk_mul_f32 v[42:43], v[44:45], v[42:43]
	v_pk_mul_f32 v[16:17], v[16:17], v[20:21]
	v_pk_mul_f32 v[20:21], v[30:31], v[22:23] op_sel:[1,0] op_sel_hi:[0,1]
	v_pk_fma_f32 v[14:15], v[30:31], v[14:15], v[20:21]
	v_pk_mul_f32 v[36:37], v[42:43], v[36:37]
	v_pk_fma_f32 v[14:15], v[0:1], v[24:25], v[14:15] op_sel_hi:[0,1,1]
	v_mul_f32_e32 v0, 0xbfb8aa3b, v28
	v_exp_f32_e32 v0, v0
	v_pk_mul_f32 v[16:17], v[16:17], v[14:15]
	v_lshlrev_b32_e32 v30, 16, v2
	v_cvt_pk_bf16_f32 v16, v16, v17
	v_add_f32_e32 v0, 1.0, v0
	v_rcp_f32_e32 v14, v0
	v_mul_f32_e32 v0, 0xbfb8aa3b, v29
	v_exp_f32_e32 v0, v0
	v_and_b32_e32 v31, 0xffff0000, v2
	v_mul_f32_e32 v2, 0xbfb8aa3b, v30
	v_exp_f32_e32 v2, v2
	v_add_f32_e32 v0, 1.0, v0
	v_rcp_f32_e32 v15, v0
	v_lshlrev_b32_e32 v24, 16, v10
	v_add_f32_e32 v2, 1.0, v2
	v_rcp_f32_e32 v32, v2
	v_pk_mul_f32 v[14:15], v[14:15], v[28:29]
	v_mul_f32_e32 v2, 0xbfb8aa3b, v31
	v_pk_mul_f32 v[20:21], v[14:15], v[26:27]
	v_cvt_pk_bf16_f32 v14, v36, v37
	v_cvt_pk_bf16_f32 v15, v18, v19
	v_cvt_pk_bf16_f32 v17, v20, v21
	global_store_dwordx4 v[54:55], v[14:17], off offset:1664 sc1
	ds_read_b128 v[20:23], v67
	ds_read_b32 v0, v219 offset:128
	v_exp_f32_e32 v2, v2
	v_and_b32_e32 v27, 0xffff0000, v10
	v_lshlrev_b32_e32 v28, 16, v6
	s_waitcnt lgkmcnt(0)
	v_and_b32_e32 v25, 0xffff0000, v20
	v_max3_f32 v16, v0, v69, v68
	v_sub_f32_e32 v0, v0, v16
	v_exp_f32_e32 v15, v0
	v_sub_f32_e32 v0, v69, v16
	v_exp_f32_e32 v14, v0
	v_sub_f32_e32 v0, v68, v16
	v_exp_f32_e32 v0, v0
	v_add_f32_e32 v2, 1.0, v2
	v_add_f32_e32 v16, v15, v14
	v_rcp_f32_e32 v33, v2
	v_add_f32_e32 v16, v0, v16
	v_rcp_f32_e32 v16, v16
	v_lshlrev_b32_e32 v2, 16, v3
	v_and_b32_e32 v3, 0xffff0000, v3
	v_lshlrev_b32_e32 v26, 16, v20
	v_mul_f32_e32 v0, v0, v16
	v_pk_mul_f32 v[18:19], v[14:15], v[16:17] op_sel_hi:[1,0]
	v_lshlrev_b32_e32 v16, 16, v23
	v_and_b32_e32 v17, 0xffff0000, v13
	v_lshlrev_b32_e32 v14, 16, v13
	v_and_b32_e32 v15, 0xffff0000, v23
	v_pk_mul_f32 v[16:17], v[18:19], v[16:17] op_sel:[1,0] op_sel_hi:[0,1]
	v_pk_fma_f32 v[14:15], v[18:19], v[14:15], v[16:17]
	v_lshlrev_b32_e32 v16, 16, v9
	v_and_b32_e32 v17, 0xffff0000, v9
	v_pk_fma_f32 v[14:15], v[0:1], v[16:17], v[14:15] op_sel_hi:[0,1,1]
	v_lshlrev_b32_e32 v16, 16, v5
	v_and_b32_e32 v17, 0xffff0000, v5
	v_mul_f32_e32 v5, 0xbfb8aa3b, v2
	v_exp_f32_e32 v5, v5
	v_pk_mul_f32 v[26:27], v[18:19], v[26:27] op_sel:[1,0] op_sel_hi:[0,1]
	v_pk_fma_f32 v[24:25], v[18:19], v[24:25], v[26:27]
	v_and_b32_e32 v27, 0xffff0000, v21
	v_add_f32_e32 v5, 1.0, v5
	v_rcp_f32_e32 v20, v5
	v_mul_f32_e32 v5, 0xbfb8aa3b, v3
	v_exp_f32_e32 v5, v5
	v_lshlrev_b32_e32 v10, 16, v21
	v_lshlrev_b32_e32 v26, 16, v11
	v_and_b32_e32 v11, 0xffff0000, v11
	v_add_f32_e32 v5, 1.0, v5
	v_rcp_f32_e32 v21, v5
	v_pk_mul_f32 v[10:11], v[18:19], v[10:11] op_sel:[1,0] op_sel_hi:[0,1]
	v_and_b32_e32 v29, 0xffff0000, v6
	v_lshlrev_b32_e32 v6, 16, v7
	v_and_b32_e32 v7, 0xffff0000, v7
	v_pk_fma_f32 v[10:11], v[18:19], v[26:27], v[10:11]
	v_pk_mul_f32 v[2:3], v[20:21], v[2:3]
	v_pk_fma_f32 v[6:7], v[0:1], v[6:7], v[10:11] op_sel_hi:[0,1,1]
	v_pk_mul_f32 v[6:7], v[2:3], v[6:7]
	v_lshlrev_b32_e32 v2, 16, v12
	v_and_b32_e32 v11, 0xffff0000, v12
	v_lshlrev_b32_e32 v12, 16, v8
	v_and_b32_e32 v13, 0xffff0000, v8
	v_lshlrev_b32_e32 v8, 16, v4
	v_and_b32_e32 v9, 0xffff0000, v4
	v_mul_f32_e32 v4, 0xbfb8aa3b, v8
	v_mul_f32_e32 v5, 0xbfb8aa3b, v9
	v_exp_f32_e32 v4, v4
	v_exp_f32_e32 v5, v5
	v_lshlrev_b32_e32 v10, 16, v22
	v_and_b32_e32 v3, 0xffff0000, v22
	v_add_f32_e32 v4, 1.0, v4
	v_add_f32_e32 v5, 1.0, v5
	v_rcp_f32_e32 v4, v4
	v_rcp_f32_e32 v5, v5
	v_pk_fma_f32 v[24:25], v[0:1], v[28:29], v[24:25] op_sel_hi:[0,1,1]
	v_pk_mul_f32 v[30:31], v[32:33], v[30:31]
	v_pk_mul_f32 v[4:5], v[4:5], v[8:9]
	v_pk_mul_f32 v[8:9], v[18:19], v[10:11] op_sel:[1,0] op_sel_hi:[0,1]
	v_pk_fma_f32 v[2:3], v[18:19], v[2:3], v[8:9]
	v_pk_mul_f32 v[24:25], v[30:31], v[24:25]
	v_pk_fma_f32 v[2:3], v[0:1], v[12:13], v[2:3] op_sel_hi:[0,1,1]
	v_mul_f32_e32 v0, 0xbfb8aa3b, v16
	v_exp_f32_e32 v0, v0
	v_pk_mul_f32 v[4:5], v[4:5], v[2:3]
	v_add_f32_e32 v0, 1.0, v0
	v_rcp_f32_e32 v2, v0
	v_mul_f32_e32 v0, 0xbfb8aa3b, v17
	v_exp_f32_e32 v0, v0
	v_cvt_pk_bf16_f32 v4, v4, v5
	v_add_f32_e32 v0, 1.0, v0
	v_rcp_f32_e32 v3, v0
	s_nop 0
	v_pk_mul_f32 v[2:3], v[2:3], v[16:17]
	s_nop 0
	v_pk_mul_f32 v[8:9], v[2:3], v[14:15]
	v_cvt_pk_bf16_f32 v2, v24, v25
	v_cvt_pk_bf16_f32 v3, v6, v7
	v_cvt_pk_bf16_f32 v5, v8, v9
	global_store_dwordx4 v[56:57], v[2:5], off offset:1664 sc1
	s_cbranch_vccz .LBB0_707
